# v75 + DPP cross-lane adds replace 96 serialized ds_bpermute reductions per item in the sample scan
# speedup vs baseline: 1.0110x; 1.0027x over previous
.LBB0_826:
	s_waitcnt lgkmcnt(0)
	s_barrier
	ds_read_b128 v[150:153], v49 offset:16384
	ds_read_b128 v[138:141], v49 offset:16400
	ds_read_b128 v[70:73], v49 offset:16416
	ds_read_b128 v[66:69], v49 offset:16432
	ds_read_b128 v[162:165], v49 offset:16512
	ds_read2st64_b32 v[154:155], v201 offset1:1
	s_lshl_b32 s7, s63, 2
	s_lshl_b64 s[0:1], s[0:1], 20
	s_add_u32 s0, s34, s0
	s_waitcnt lgkmcnt(1)
	v_mov_b32_e32 v182, v165
	s_waitcnt lgkmcnt(0)
	v_mul_f32_e32 v174, v150, v154
	v_mul_f32_e32 v176, v151, v155
	ds_read2st64_b32 v[150:151], v201 offset0:2 offset1:3
	ds_read_b128 v[166:169], v215 offset:8192
	ds_read_b128 v[170:173], v215 offset:12288
	s_addc_u32 s1, s35, s1
	s_lshl_b32 s21, s63, 17
	v_ashrrev_i32_e32 v149, 31, v148
	s_waitcnt lgkmcnt(2)
	v_mul_f32_e32 v178, v152, v150
	v_mul_f32_e32 v180, v153, v151
	s_waitcnt lgkmcnt(1)
	v_pk_mul_f32 v[150:151], v[174:175], v[168:169] op_sel_hi:[0,1]
	v_pk_mul_f32 v[152:153], v[174:175], v[166:167] op_sel_hi:[0,1]
	v_pk_fma_f32 v[150:151], v[124:125], v[162:163], v[150:151] op_sel_hi:[1,0,1]
	v_pk_fma_f32 v[152:153], v[122:123], v[162:163], v[152:153] op_sel_hi:[1,0,1]
	s_waitcnt lgkmcnt(0)
	v_mul_f32_e32 v123, v173, v151
	v_mul_f32_e32 v122, v171, v153
	v_fmac_f32_e32 v122, v170, v152
	v_fmac_f32_e32 v123, v172, v150
	v_add_f32_e32 v122, v122, v123
	v_add_f32_e32 v175, 0, v122
	v_pk_mul_f32 v[122:123], v[168:169], v[176:177] op_sel_hi:[1,0]
	v_pk_mul_f32 v[124:125], v[166:167], v[176:177] op_sel_hi:[1,0]
	v_pk_fma_f32 v[154:155], v[128:129], v[162:163], v[122:123] op_sel:[0,1,0]
	v_pk_fma_f32 v[156:157], v[126:127], v[162:163], v[124:125] op_sel:[0,1,0]
	v_mul_f32_e32 v123, v173, v155
	v_mul_f32_e32 v122, v171, v157
	v_fmac_f32_e32 v122, v170, v156
	v_fmac_f32_e32 v123, v172, v154
	v_add_f32_e32 v122, v122, v123
	v_add_f32_e32 v177, 0, v122
	v_pk_mul_f32 v[122:123], v[168:169], v[178:179] op_sel_hi:[1,0]
	v_pk_mul_f32 v[124:125], v[166:167], v[178:179] op_sel_hi:[1,0]
	v_pk_fma_f32 v[158:159], v[132:133], v[164:165], v[122:123] op_sel_hi:[1,0,1]
	v_pk_fma_f32 v[160:161], v[130:131], v[164:165], v[124:125] op_sel_hi:[1,0,1]
	v_mul_f32_e32 v123, v173, v159
	v_mul_f32_e32 v122, v171, v161
	v_fmac_f32_e32 v122, v170, v160
	v_fmac_f32_e32 v123, v172, v158
	v_add_f32_e32 v122, v122, v123
	v_add_f32_e32 v179, 0, v122
	v_pk_mul_f32 v[122:123], v[168:169], v[180:181] op_sel_hi:[1,0]
	v_pk_mul_f32 v[124:125], v[166:167], v[180:181] op_sel_hi:[1,0]
	v_pk_fma_f32 v[136:137], v[136:137], v[182:183], v[122:123] op_sel_hi:[1,0,1]
	v_pk_fma_f32 v[134:135], v[134:135], v[182:183], v[124:125] op_sel_hi:[1,0,1]
	v_mul_f32_e32 v123, v173, v137
	v_mul_f32_e32 v122, v171, v135
	v_fmac_f32_e32 v122, v170, v134
	v_fmac_f32_e32 v123, v172, v136
	ds_read_b128 v[166:169], v215 offset:8320
	ds_read_b128 v[170:173], v215 offset:12416
	v_add_f32_e32 v122, v122, v123
	v_add_f32_e32 v165, 0, v122
	s_add_u32 s0, s0, s21
	s_waitcnt lgkmcnt(1)
	v_pk_mul_f32 v[122:123], v[174:175], v[168:169] op_sel_hi:[0,1]
	v_pk_mul_f32 v[124:125], v[174:175], v[166:167] op_sel_hi:[0,1]
	v_pk_fma_f32 v[130:131], v[108:109], v[162:163], v[122:123] op_sel_hi:[1,0,1]
	v_pk_fma_f32 v[132:133], v[106:107], v[162:163], v[124:125] op_sel_hi:[1,0,1]
	s_waitcnt lgkmcnt(0)
	v_mul_f32_e32 v107, v173, v131
	v_mul_f32_e32 v106, v171, v133
	v_fmac_f32_e32 v106, v170, v132
	v_fmac_f32_e32 v107, v172, v130
	v_add_f32_e32 v106, v106, v107
	v_add_f32_e32 v175, v175, v106
	v_pk_mul_f32 v[106:107], v[176:177], v[168:169] op_sel_hi:[0,1]
	v_pk_mul_f32 v[108:109], v[176:177], v[166:167] op_sel_hi:[0,1]
	v_pk_fma_f32 v[126:127], v[112:113], v[162:163], v[106:107] op_sel:[0,1,0]
	v_pk_fma_f32 v[128:129], v[110:111], v[162:163], v[108:109] op_sel:[0,1,0]
	v_mul_f32_e32 v107, v173, v127
	v_mul_f32_e32 v106, v171, v129
	v_fmac_f32_e32 v106, v170, v128
	v_fmac_f32_e32 v107, v172, v126
	v_add_f32_e32 v106, v106, v107
	v_add_f32_e32 v177, v177, v106
	v_pk_mul_f32 v[106:107], v[178:179], v[168:169] op_sel_hi:[0,1]
	v_pk_mul_f32 v[108:109], v[178:179], v[166:167] op_sel_hi:[0,1]
	v_pk_fma_f32 v[122:123], v[116:117], v[164:165], v[106:107] op_sel_hi:[1,0,1]
	v_pk_fma_f32 v[124:125], v[114:115], v[164:165], v[108:109] op_sel_hi:[1,0,1]
	v_mul_f32_e32 v107, v173, v123
	v_mul_f32_e32 v106, v171, v125
	v_fmac_f32_e32 v106, v170, v124
	v_fmac_f32_e32 v107, v172, v122
	v_add_f32_e32 v106, v106, v107
	v_add_f32_e32 v179, v179, v106
	v_pk_mul_f32 v[106:107], v[168:169], v[180:181] op_sel_hi:[1,0]
	v_pk_mul_f32 v[108:109], v[166:167], v[180:181] op_sel_hi:[1,0]
	v_pk_fma_f32 v[114:115], v[120:121], v[182:183], v[106:107] op_sel_hi:[1,0,1]
	v_pk_fma_f32 v[116:117], v[118:119], v[182:183], v[108:109] op_sel_hi:[1,0,1]
	ds_read_b128 v[118:121], v215 offset:8448
	ds_read_b128 v[166:169], v215 offset:12544
	v_mul_f32_e32 v106, v171, v117
	v_mul_f32_e32 v107, v173, v115
	v_fmac_f32_e32 v106, v170, v116
	v_fmac_f32_e32 v107, v172, v114
	v_add_f32_e32 v106, v106, v107
	v_add_f32_e32 v165, v106, v165
	s_waitcnt lgkmcnt(1)
	v_pk_mul_f32 v[106:107], v[174:175], v[120:121] op_sel_hi:[0,1]
	v_pk_mul_f32 v[108:109], v[174:175], v[118:119] op_sel_hi:[0,1]
	v_pk_fma_f32 v[106:107], v[92:93], v[162:163], v[106:107] op_sel_hi:[1,0,1]
	v_pk_fma_f32 v[108:109], v[90:91], v[162:163], v[108:109] op_sel_hi:[1,0,1]
	s_waitcnt lgkmcnt(0)
	v_mul_f32_e32 v91, v169, v107
	v_mul_f32_e32 v90, v167, v109
	v_fmac_f32_e32 v90, v166, v108
	v_fmac_f32_e32 v91, v168, v106
	v_add_f32_e32 v90, v90, v91
	v_add_f32_e32 v170, v175, v90
	v_pk_mul_f32 v[90:91], v[176:177], v[120:121] op_sel_hi:[0,1]
	v_pk_mul_f32 v[92:93], v[176:177], v[118:119] op_sel_hi:[0,1]
	v_pk_fma_f32 v[110:111], v[96:97], v[162:163], v[90:91] op_sel:[0,1,0]
	v_pk_fma_f32 v[112:113], v[94:95], v[162:163], v[92:93] op_sel:[0,1,0]
	v_mul_f32_e32 v91, v169, v111
	v_mul_f32_e32 v90, v167, v113
	v_fmac_f32_e32 v90, v166, v112
	v_fmac_f32_e32 v91, v168, v110
	v_add_f32_e32 v90, v90, v91
	v_add_f32_e32 v171, v177, v90
	v_pk_mul_f32 v[90:91], v[178:179], v[120:121] op_sel_hi:[0,1]
	v_pk_mul_f32 v[92:93], v[178:179], v[118:119] op_sel_hi:[0,1]
	v_pk_fma_f32 v[100:101], v[100:101], v[164:165], v[90:91] op_sel_hi:[1,0,1]
	v_pk_fma_f32 v[98:99], v[98:99], v[164:165], v[92:93] op_sel_hi:[1,0,1]
	v_mul_f32_e32 v91, v169, v101
	v_mul_f32_e32 v90, v167, v99
	v_fmac_f32_e32 v90, v166, v98
	v_fmac_f32_e32 v91, v168, v100
	v_add_f32_e32 v90, v90, v91
	v_add_f32_e32 v172, v179, v90
	v_pk_mul_f32 v[90:91], v[180:181], v[120:121] op_sel_hi:[0,1]
	v_pk_mul_f32 v[92:93], v[180:181], v[118:119] op_sel_hi:[0,1]
	v_pk_fma_f32 v[104:105], v[104:105], v[182:183], v[90:91] op_sel_hi:[1,0,1]
	v_pk_fma_f32 v[102:103], v[102:103], v[182:183], v[92:93] op_sel_hi:[1,0,1]
	v_mul_f32_e32 v91, v169, v105
	v_mul_f32_e32 v90, v167, v103
	v_fmac_f32_e32 v90, v166, v102
	v_fmac_f32_e32 v91, v168, v104
	ds_read_b128 v[118:121], v215 offset:8576
	ds_read_b128 v[166:169], v215 offset:12672
	v_add_f32_e32 v90, v90, v91
	v_add_f32_e32 v165, v165, v90
	s_addc_u32 s1, s1, 0
	s_waitcnt lgkmcnt(1)
	v_pk_mul_f32 v[90:91], v[174:175], v[120:121] op_sel_hi:[0,1]
	v_pk_mul_f32 v[92:93], v[174:175], v[118:119] op_sel_hi:[0,1]
	v_pk_fma_f32 v[94:95], v[76:77], v[162:163], v[90:91] op_sel_hi:[1,0,1]
	v_pk_fma_f32 v[96:97], v[74:75], v[162:163], v[92:93] op_sel_hi:[1,0,1]
	s_waitcnt lgkmcnt(0)
	v_mul_f32_e32 v75, v169, v95
	v_mul_f32_e32 v74, v167, v97
	v_fmac_f32_e32 v74, v166, v96
	v_fmac_f32_e32 v75, v168, v94
	v_add_f32_e32 v74, v74, v75
	v_add_f32_e32 v170, v170, v74
	v_pk_mul_f32 v[74:75], v[176:177], v[120:121] op_sel_hi:[0,1]
	v_pk_mul_f32 v[76:77], v[176:177], v[118:119] op_sel_hi:[0,1]
	v_pk_fma_f32 v[90:91], v[80:81], v[162:163], v[74:75] op_sel:[0,1,0]
	v_pk_fma_f32 v[92:93], v[78:79], v[162:163], v[76:77] op_sel:[0,1,0]
	v_mul_f32_e32 v75, v169, v91
	v_mul_f32_e32 v74, v167, v93
	v_fmac_f32_e32 v74, v166, v92
	v_fmac_f32_e32 v75, v168, v90
	v_add_f32_e32 v74, v74, v75
	v_add_f32_e32 v162, v171, v74
	v_pk_mul_f32 v[74:75], v[178:179], v[120:121] op_sel_hi:[0,1]
	v_pk_mul_f32 v[76:77], v[178:179], v[118:119] op_sel_hi:[0,1]
	v_pk_fma_f32 v[84:85], v[84:85], v[164:165], v[74:75] op_sel_hi:[1,0,1]
	v_pk_fma_f32 v[82:83], v[82:83], v[164:165], v[76:77] op_sel_hi:[1,0,1]
	v_mul_f32_e32 v75, v169, v85
	v_mul_f32_e32 v74, v167, v83
	v_fmac_f32_e32 v74, v166, v82
	v_fmac_f32_e32 v75, v168, v84
	v_add_f32_e32 v74, v74, v75
	v_add_f32_e32 v163, v172, v74
	v_pk_mul_f32 v[74:75], v[180:181], v[120:121] op_sel_hi:[0,1]
	v_pk_mul_f32 v[76:77], v[180:181], v[118:119] op_sel_hi:[0,1]
	v_pk_fma_f32 v[78:79], v[88:89], v[182:183], v[74:75] op_sel_hi:[1,0,1]
	v_pk_fma_f32 v[80:81], v[86:87], v[182:183], v[76:77] op_sel_hi:[1,0,1]
	v_mul_f32_e32 v75, v169, v79
	v_mul_f32_e32 v74, v167, v81
	v_fmac_f32_e32 v74, v166, v80
	v_fmac_f32_e32 v75, v168, v78
	v_add_f32_e32 v74, v74, v75
	s_nop 1
	v_add_f32_e32 v74, v165, v74
	s_or_b32 s64, s7, s11
	v_readlane_b32 s24, v252, 53
	v_readlane_b32 s25, v252, 54
	s_waitcnt lgkmcnt(0)
	v_add_f32_dpp v75, v170, v170 quad_perm:[1,0,3,2] row_mask:0xf bank_mask:0xf
	s_nop 1
	v_readlane_b32 s26, v252, 55
	v_readlane_b32 s27, v252, 56
	s_waitcnt lgkmcnt(0)
	v_add_f32_dpp v75, v75, v75 quad_perm:[2,3,0,1] row_mask:0xf bank_mask:0xf
	s_nop 1
	s_waitcnt lgkmcnt(0)
	v_add_f32_dpp v75, v75, v75 row_half_mirror row_mask:0xf bank_mask:0xf
	v_cndmask_b32_e64 v121, 0, v75, s[46:47]
	s_nop 1
	s_waitcnt lgkmcnt(0)
	v_add_f32_dpp v75, v162, v162 quad_perm:[1,0,3,2] row_mask:0xf bank_mask:0xf
	s_nop 1
	s_waitcnt lgkmcnt(0)
	v_add_f32_dpp v75, v75, v75 quad_perm:[2,3,0,1] row_mask:0xf bank_mask:0xf
	s_nop 1
	s_waitcnt lgkmcnt(0)
	v_add_f32_dpp v75, v75, v75 row_half_mirror row_mask:0xf bank_mask:0xf
	v_cndmask_b32_e64 v119, 0, v75, s[46:47]
	s_nop 1
	s_waitcnt lgkmcnt(0)
	v_add_f32_dpp v75, v163, v163 quad_perm:[1,0,3,2] row_mask:0xf bank_mask:0xf
	s_nop 1
	s_waitcnt lgkmcnt(0)
	v_add_f32_dpp v75, v75, v75 quad_perm:[2,3,0,1] row_mask:0xf bank_mask:0xf
	s_nop 1
	s_waitcnt lgkmcnt(0)
	v_add_f32_dpp v75, v75, v75 row_half_mirror row_mask:0xf bank_mask:0xf
	v_cndmask_b32_e64 v89, 0, v75, s[46:47]
	s_nop 1
	s_waitcnt lgkmcnt(0)
	v_add_f32_dpp v74, v74, v74 quad_perm:[1,0,3,2] row_mask:0xf bank_mask:0xf
	s_nop 1
	s_waitcnt lgkmcnt(0)
	v_add_f32_dpp v74, v74, v74 quad_perm:[2,3,0,1] row_mask:0xf bank_mask:0xf
	s_nop 1
	s_waitcnt lgkmcnt(0)
	v_add_f32_dpp v74, v74, v74 row_half_mirror row_mask:0xf bank_mask:0xf
	v_cndmask_b32_e64 v87, 0, v74, s[46:47]
	ds_read_b128 v[74:77], v49 offset:16528
	ds_read2st64_b32 v[162:163], v201 offset0:4 offset1:5
	s_waitcnt lgkmcnt(1)
	v_mov_b32_e32 v176, v77
	s_waitcnt lgkmcnt(0)
	v_mul_f32_e32 v120, v138, v162
	v_mul_f32_e32 v88, v139, v163
	ds_read2st64_b32 v[138:139], v201 offset0:6 offset1:7
	ds_read_b128 v[162:165], v215 offset:8704
	ds_read_b128 v[166:169], v215 offset:12800
	ds_read_b128 v[172:175], v215 offset:8832
	ds_read_b128 v[178:181], v215 offset:12928
	s_waitcnt lgkmcnt(4)
	v_mul_f32_e32 v118, v140, v138
	v_mul_f32_e32 v86, v141, v139
	s_waitcnt lgkmcnt(3)
	v_pk_mul_f32 v[138:139], v[120:121], v[164:165] op_sel_hi:[0,1]
	v_pk_mul_f32 v[140:141], v[120:121], v[162:163] op_sel_hi:[0,1]
	v_pk_fma_f32 v[138:139], v[150:151], v[74:75], v[138:139] op_sel_hi:[1,0,1]
	v_pk_fma_f32 v[140:141], v[152:153], v[74:75], v[140:141] op_sel_hi:[1,0,1]
	s_waitcnt lgkmcnt(2)
	v_mul_f32_e32 v151, v169, v139
	v_mul_f32_e32 v150, v167, v141
	v_fmac_f32_e32 v150, v166, v140
	v_fmac_f32_e32 v151, v168, v138
	v_add_f32_e32 v150, v150, v151
	v_add_f32_e32 v170, 0, v150
	v_pk_mul_f32 v[150:151], v[164:165], v[88:89] op_sel_hi:[1,0]
	v_pk_mul_f32 v[152:153], v[162:163], v[88:89] op_sel_hi:[1,0]
	v_pk_fma_f32 v[150:151], v[154:155], v[74:75], v[150:151] op_sel:[0,1,0]
	v_pk_fma_f32 v[152:153], v[156:157], v[74:75], v[152:153] op_sel:[0,1,0]
	v_mul_f32_e32 v155, v169, v151
	v_mul_f32_e32 v154, v167, v153
	v_fmac_f32_e32 v154, v166, v152
	v_fmac_f32_e32 v155, v168, v150
	v_add_f32_e32 v154, v154, v155
	v_add_f32_e32 v171, 0, v154
	v_pk_mul_f32 v[154:155], v[164:165], v[118:119] op_sel_hi:[1,0]
	v_pk_mul_f32 v[156:157], v[162:163], v[118:119] op_sel_hi:[1,0]
	v_pk_fma_f32 v[154:155], v[158:159], v[76:77], v[154:155] op_sel_hi:[1,0,1]
	v_pk_fma_f32 v[156:157], v[160:161], v[76:77], v[156:157] op_sel_hi:[1,0,1]
	v_mul_f32_e32 v159, v169, v155
	v_mul_f32_e32 v158, v167, v157
	v_fmac_f32_e32 v158, v166, v156
	v_fmac_f32_e32 v159, v168, v154
	v_add_f32_e32 v158, v158, v159
	v_add_f32_e32 v177, 0, v158
	v_pk_mul_f32 v[158:159], v[164:165], v[86:87] op_sel_hi:[1,0]
	v_pk_mul_f32 v[160:161], v[162:163], v[86:87] op_sel_hi:[1,0]
	v_pk_fma_f32 v[136:137], v[136:137], v[176:177], v[158:159] op_sel_hi:[1,0,1]
	v_pk_fma_f32 v[158:159], v[134:135], v[176:177], v[160:161] op_sel_hi:[1,0,1]
	v_mul_f32_e32 v134, v169, v137
	v_mul_f32_e32 v77, v167, v159
	v_fmac_f32_e32 v77, v166, v158
	v_fmac_f32_e32 v134, v168, v136
	v_add_f32_e32 v77, v77, v134
	s_waitcnt lgkmcnt(1)
	v_pk_mul_f32 v[134:135], v[120:121], v[174:175] op_sel_hi:[0,1]
	v_pk_mul_f32 v[162:163], v[120:121], v[172:173] op_sel_hi:[0,1]
	v_pk_fma_f32 v[160:161], v[130:131], v[74:75], v[134:135] op_sel_hi:[1,0,1]
	v_pk_fma_f32 v[162:163], v[132:133], v[74:75], v[162:163] op_sel_hi:[1,0,1]
	s_waitcnt lgkmcnt(0)
	v_mul_f32_e32 v131, v181, v161
	v_mul_f32_e32 v130, v179, v163
	v_fmac_f32_e32 v130, v178, v162
	v_fmac_f32_e32 v131, v180, v160
	v_add_f32_e32 v130, v130, v131
	v_add_f32_e32 v134, v170, v130
	v_pk_mul_f32 v[130:131], v[88:89], v[174:175] op_sel_hi:[0,1]
	v_pk_mul_f32 v[132:133], v[88:89], v[172:173] op_sel_hi:[0,1]
	v_pk_fma_f32 v[164:165], v[126:127], v[74:75], v[130:131] op_sel:[0,1,0]
	v_pk_fma_f32 v[166:167], v[128:129], v[74:75], v[132:133] op_sel:[0,1,0]
	v_mul_f32_e32 v127, v181, v165
	v_mul_f32_e32 v126, v179, v167
	v_fmac_f32_e32 v126, v178, v166
	v_fmac_f32_e32 v127, v180, v164
	v_add_f32_e32 v126, v126, v127
	v_add_f32_e32 v77, 0, v77
	v_add_f32_e32 v130, v171, v126
	v_pk_mul_f32 v[126:127], v[118:119], v[174:175] op_sel_hi:[0,1]
	v_pk_mul_f32 v[128:129], v[118:119], v[172:173] op_sel_hi:[0,1]
	v_pk_fma_f32 v[168:169], v[122:123], v[76:77], v[126:127] op_sel_hi:[1,0,1]
	v_pk_fma_f32 v[170:171], v[124:125], v[76:77], v[128:129] op_sel_hi:[1,0,1]
	v_mul_f32_e32 v123, v181, v169
	v_mul_f32_e32 v122, v179, v171
	v_fmac_f32_e32 v122, v178, v170
	v_fmac_f32_e32 v123, v180, v168
	v_add_f32_e32 v122, v122, v123
	v_add_f32_e32 v131, v177, v122
	v_pk_mul_f32 v[122:123], v[174:175], v[86:87] op_sel_hi:[1,0]
	v_pk_mul_f32 v[124:125], v[172:173], v[86:87] op_sel_hi:[1,0]
	v_pk_fma_f32 v[172:173], v[114:115], v[176:177], v[122:123] op_sel_hi:[1,0,1]
	v_pk_fma_f32 v[174:175], v[116:117], v[176:177], v[124:125] op_sel_hi:[1,0,1]
	v_mul_f32_e32 v115, v181, v173
	v_mul_f32_e32 v114, v179, v175
	v_fmac_f32_e32 v114, v178, v174
	v_fmac_f32_e32 v115, v180, v172
	v_add_f32_e32 v114, v114, v115
	v_add_f32_e32 v77, v114, v77
	ds_read_b128 v[114:117], v215 offset:8960
	ds_read_b128 v[122:125], v215 offset:13056
	s_waitcnt lgkmcnt(1)
	v_pk_mul_f32 v[126:127], v[120:121], v[116:117] op_sel_hi:[0,1]
	v_pk_mul_f32 v[128:129], v[120:121], v[114:115] op_sel_hi:[0,1]
	v_pk_fma_f32 v[178:179], v[106:107], v[74:75], v[126:127] op_sel_hi:[1,0,1]
	v_pk_fma_f32 v[180:181], v[108:109], v[74:75], v[128:129] op_sel_hi:[1,0,1]
	s_waitcnt lgkmcnt(0)
	v_mul_f32_e32 v107, v125, v179
	v_mul_f32_e32 v106, v123, v181
	v_fmac_f32_e32 v106, v122, v180
	v_fmac_f32_e32 v107, v124, v178
	v_add_f32_e32 v106, v106, v107
	v_add_f32_e32 v126, v134, v106
	v_pk_mul_f32 v[106:107], v[88:89], v[116:117] op_sel_hi:[0,1]
	v_pk_mul_f32 v[108:109], v[88:89], v[114:115] op_sel_hi:[0,1]
	v_pk_fma_f32 v[182:183], v[110:111], v[74:75], v[106:107] op_sel:[0,1,0]
	v_pk_fma_f32 v[184:185], v[112:113], v[74:75], v[108:109] op_sel:[0,1,0]
	v_mul_f32_e32 v107, v125, v183
	v_mul_f32_e32 v106, v123, v185
	v_fmac_f32_e32 v106, v122, v184
	v_fmac_f32_e32 v107, v124, v182
	v_add_f32_e32 v106, v106, v107
	v_add_f32_e32 v127, v130, v106
	v_pk_mul_f32 v[106:107], v[118:119], v[116:117] op_sel_hi:[0,1]
	v_pk_mul_f32 v[108:109], v[118:119], v[114:115] op_sel_hi:[0,1]
	v_pk_fma_f32 v[100:101], v[100:101], v[76:77], v[106:107] op_sel_hi:[1,0,1]
	v_pk_fma_f32 v[186:187], v[98:99], v[76:77], v[108:109] op_sel_hi:[1,0,1]
	v_mul_f32_e32 v99, v125, v101
	v_mul_f32_e32 v98, v123, v187
	v_fmac_f32_e32 v98, v122, v186
	v_fmac_f32_e32 v99, v124, v100
	v_add_f32_e32 v98, v98, v99
	v_add_f32_e32 v128, v131, v98
	v_pk_mul_f32 v[98:99], v[86:87], v[116:117] op_sel_hi:[0,1]
	v_pk_mul_f32 v[106:107], v[86:87], v[114:115] op_sel_hi:[0,1]
	v_pk_fma_f32 v[104:105], v[104:105], v[176:177], v[98:99] op_sel_hi:[1,0,1]
	v_pk_fma_f32 v[188:189], v[102:103], v[176:177], v[106:107] op_sel_hi:[1,0,1]
	ds_read_b128 v[106:109], v215 offset:9088
	ds_read_b128 v[110:113], v215 offset:13184
	v_mul_f32_e32 v98, v123, v189
	v_mul_f32_e32 v99, v125, v105
	v_fmac_f32_e32 v98, v122, v188
	v_fmac_f32_e32 v99, v124, v104
	v_add_f32_e32 v98, v98, v99
	v_add_f32_e32 v114, v77, v98
	s_waitcnt lgkmcnt(1)
	v_pk_mul_f32 v[98:99], v[120:121], v[108:109] op_sel_hi:[0,1]
	v_pk_mul_f32 v[102:103], v[120:121], v[106:107] op_sel_hi:[0,1]
	v_pk_fma_f32 v[190:191], v[94:95], v[74:75], v[98:99] op_sel_hi:[1,0,1]
	v_pk_fma_f32 v[192:193], v[96:97], v[74:75], v[102:103] op_sel_hi:[1,0,1]
	s_waitcnt lgkmcnt(0)
	v_mul_f32_e32 v94, v113, v191
	v_mul_f32_e32 v77, v111, v193
	v_fmac_f32_e32 v77, v110, v192
	v_fmac_f32_e32 v94, v112, v190
	v_add_f32_e32 v77, v77, v94
	v_pk_mul_f32 v[94:95], v[88:89], v[108:109] op_sel_hi:[0,1]
	v_pk_mul_f32 v[96:97], v[88:89], v[106:107] op_sel_hi:[0,1]
	v_pk_fma_f32 v[194:195], v[90:91], v[74:75], v[94:95] op_sel:[0,1,0]
	v_pk_fma_f32 v[74:75], v[92:93], v[74:75], v[96:97] op_sel:[0,1,0]
	v_add_f32_e32 v98, v126, v77
	v_mul_f32_e32 v77, v111, v75
	v_mul_f32_e32 v88, v113, v195
	v_fmac_f32_e32 v77, v110, v74
	v_fmac_f32_e32 v88, v112, v194
	v_add_f32_e32 v77, v77, v88
	v_pk_mul_f32 v[90:91], v[118:119], v[108:109] op_sel_hi:[0,1]
	v_pk_mul_f32 v[92:93], v[118:119], v[106:107] op_sel_hi:[0,1]
	v_add_f32_e32 v88, v127, v77
	v_pk_fma_f32 v[196:197], v[84:85], v[76:77], v[90:91] op_sel_hi:[1,0,1]
	v_pk_fma_f32 v[76:77], v[82:83], v[76:77], v[92:93] op_sel_hi:[1,0,1]
	v_mul_f32_e32 v83, v113, v197
	v_mul_f32_e32 v82, v111, v77
	v_fmac_f32_e32 v82, v110, v76
	v_fmac_f32_e32 v83, v112, v196
	v_add_f32_e32 v82, v82, v83
	v_add_f32_e32 v90, v128, v82
	v_pk_mul_f32 v[82:83], v[86:87], v[108:109] op_sel_hi:[0,1]
	v_pk_mul_f32 v[84:85], v[86:87], v[106:107] op_sel_hi:[0,1]
	v_pk_fma_f32 v[198:199], v[78:79], v[176:177], v[82:83] op_sel_hi:[1,0,1]
	v_pk_fma_f32 v[176:177], v[80:81], v[176:177], v[84:85] op_sel_hi:[1,0,1]
	v_mul_f32_e32 v79, v113, v199
	v_mul_f32_e32 v78, v111, v177
	v_fmac_f32_e32 v78, v110, v176
	v_fmac_f32_e32 v79, v112, v198
	v_add_f32_e32 v78, v78, v79
	s_nop 1
	v_add_f32_e32 v78, v114, v78
	s_waitcnt lgkmcnt(0)
	v_add_f32_dpp v79, v98, v98 quad_perm:[1,0,3,2] row_mask:0xf bank_mask:0xf
	s_nop 1
	s_waitcnt lgkmcnt(0)
	v_add_f32_dpp v79, v79, v79 quad_perm:[2,3,0,1] row_mask:0xf bank_mask:0xf
	s_nop 1
	s_waitcnt lgkmcnt(0)
	v_add_f32_dpp v79, v79, v79 row_half_mirror row_mask:0xf bank_mask:0xf
	v_cndmask_b32_e64 v225, v121, v79, s[48:49]
	s_nop 1
	s_waitcnt lgkmcnt(0)
	v_add_f32_dpp v79, v88, v88 quad_perm:[1,0,3,2] row_mask:0xf bank_mask:0xf
	s_nop 1
	s_waitcnt lgkmcnt(0)
	v_add_f32_dpp v79, v79, v79 quad_perm:[2,3,0,1] row_mask:0xf bank_mask:0xf
	s_nop 1
	s_waitcnt lgkmcnt(0)
	v_add_f32_dpp v79, v79, v79 row_half_mirror row_mask:0xf bank_mask:0xf
	v_cndmask_b32_e64 v227, v119, v79, s[48:49]
	s_nop 1
	s_waitcnt lgkmcnt(0)
	v_add_f32_dpp v79, v90, v90 quad_perm:[1,0,3,2] row_mask:0xf bank_mask:0xf
	s_nop 1
	s_waitcnt lgkmcnt(0)
	v_add_f32_dpp v79, v79, v79 quad_perm:[2,3,0,1] row_mask:0xf bank_mask:0xf
	s_nop 1
	s_waitcnt lgkmcnt(0)
	v_add_f32_dpp v79, v79, v79 row_half_mirror row_mask:0xf bank_mask:0xf
	v_cndmask_b32_e64 v229, v89, v79, s[48:49]
	s_nop 1
	s_waitcnt lgkmcnt(0)
	v_add_f32_dpp v78, v78, v78 quad_perm:[1,0,3,2] row_mask:0xf bank_mask:0xf
	s_nop 1
	s_waitcnt lgkmcnt(0)
	v_add_f32_dpp v78, v78, v78 quad_perm:[2,3,0,1] row_mask:0xf bank_mask:0xf
	s_nop 1
	s_waitcnt lgkmcnt(0)
	v_add_f32_dpp v78, v78, v78 row_half_mirror row_mask:0xf bank_mask:0xf
	v_cndmask_b32_e64 v230, v87, v78, s[48:49]
	ds_read_b128 v[78:81], v49 offset:16544
	ds_read2st64_b32 v[82:83], v201 offset0:8 offset1:9
	s_waitcnt lgkmcnt(0)
	v_mul_f32_e32 v86, v70, v82
	v_mul_f32_e32 v224, v71, v83
	ds_read2st64_b32 v[70:71], v201 offset0:10 offset1:11
	s_waitcnt lgkmcnt(0)
	v_mul_f32_e32 v226, v72, v70
	v_mul_f32_e32 v228, v73, v71
	ds_read_b128 v[70:73], v215 offset:9216
	ds_read_b128 v[82:85], v215 offset:13312
	s_waitcnt lgkmcnt(1)
	v_pk_mul_f32 v[88:89], v[86:87], v[72:73] op_sel_hi:[0,1]
	v_pk_mul_f32 v[90:91], v[86:87], v[70:71] op_sel_hi:[0,1]
	v_pk_fma_f32 v[122:123], v[138:139], v[78:79], v[88:89] op_sel_hi:[1,0,1]
	v_pk_fma_f32 v[124:125], v[140:141], v[78:79], v[90:91] op_sel_hi:[1,0,1]
	s_waitcnt lgkmcnt(0)
	v_mul_f32_e32 v88, v85, v123
	v_mul_f32_e32 v87, v83, v125
	v_fmac_f32_e32 v87, v82, v124
	v_fmac_f32_e32 v88, v84, v122
	v_add_f32_e32 v87, v87, v88
	v_pk_mul_f32 v[88:89], v[72:73], v[224:225] op_sel_hi:[1,0]
	v_pk_mul_f32 v[90:91], v[70:71], v[224:225] op_sel_hi:[1,0]
	v_pk_fma_f32 v[126:127], v[150:151], v[78:79], v[88:89] op_sel:[0,1,0]
	v_pk_fma_f32 v[128:129], v[152:153], v[78:79], v[90:91] op_sel:[0,1,0]
	v_mul_f32_e32 v89, v85, v127
	v_mul_f32_e32 v88, v83, v129
	v_fmac_f32_e32 v88, v82, v128
	v_fmac_f32_e32 v89, v84, v126
	v_add_f32_e32 v88, v88, v89
	v_add_f32_e32 v92, 0, v88
	v_pk_mul_f32 v[88:89], v[72:73], v[226:227] op_sel_hi:[1,0]
	v_pk_mul_f32 v[90:91], v[70:71], v[226:227] op_sel_hi:[1,0]
	v_pk_mul_f32 v[72:73], v[72:73], v[228:229] op_sel_hi:[1,0]
	v_pk_mul_f32 v[70:71], v[70:71], v[228:229] op_sel_hi:[1,0]
	v_mov_b32_e32 v150, v81
	v_pk_fma_f32 v[134:135], v[136:137], v[150:151], v[72:73] op_sel_hi:[1,0,1]
	v_pk_fma_f32 v[136:137], v[158:159], v[150:151], v[70:71] op_sel_hi:[1,0,1]
	v_mul_f32_e32 v71, v85, v135
	v_mul_f32_e32 v70, v83, v137
	v_pk_fma_f32 v[130:131], v[154:155], v[80:81], v[88:89] op_sel_hi:[1,0,1]
	v_pk_fma_f32 v[132:133], v[156:157], v[80:81], v[90:91] op_sel_hi:[1,0,1]
	v_fmac_f32_e32 v70, v82, v136
	v_fmac_f32_e32 v71, v84, v134
	v_mul_f32_e32 v88, v83, v133
	v_mul_f32_e32 v89, v85, v131
	v_add_f32_e32 v70, v70, v71
	v_fmac_f32_e32 v88, v82, v132
	v_fmac_f32_e32 v89, v84, v130
	v_add_f32_e32 v81, 0, v70
	ds_read_b128 v[70:73], v215 offset:9344
	ds_read_b128 v[82:85], v215 offset:13440
	v_add_f32_e32 v87, 0, v87
	v_add_f32_e32 v88, v88, v89
	v_add_f32_e32 v93, 0, v88
	s_waitcnt lgkmcnt(1)
	v_pk_mul_f32 v[88:89], v[86:87], v[72:73] op_sel_hi:[0,1]
	v_pk_mul_f32 v[90:91], v[86:87], v[70:71] op_sel_hi:[0,1]
	v_pk_fma_f32 v[118:119], v[160:161], v[78:79], v[88:89] op_sel_hi:[1,0,1]
	v_pk_fma_f32 v[120:121], v[162:163], v[78:79], v[90:91] op_sel_hi:[1,0,1]
	s_waitcnt lgkmcnt(0)
	v_mul_f32_e32 v89, v85, v119
	v_mul_f32_e32 v88, v83, v121
	v_fmac_f32_e32 v88, v82, v120
	v_fmac_f32_e32 v89, v84, v118
	v_add_f32_e32 v88, v88, v89
	v_add_f32_e32 v87, v87, v88
	v_pk_mul_f32 v[88:89], v[224:225], v[72:73] op_sel_hi:[0,1]
	v_pk_mul_f32 v[90:91], v[224:225], v[70:71] op_sel_hi:[0,1]
	v_pk_fma_f32 v[114:115], v[164:165], v[78:79], v[88:89] op_sel:[0,1,0]
	v_pk_fma_f32 v[116:117], v[166:167], v[78:79], v[90:91] op_sel:[0,1,0]
	v_mul_f32_e32 v89, v85, v115
	v_mul_f32_e32 v88, v83, v117
	v_fmac_f32_e32 v88, v82, v116
	v_fmac_f32_e32 v89, v84, v114
	v_add_f32_e32 v88, v88, v89
	v_add_f32_e32 v98, v92, v88
	v_pk_mul_f32 v[88:89], v[226:227], v[72:73] op_sel_hi:[0,1]
	v_pk_mul_f32 v[90:91], v[226:227], v[70:71] op_sel_hi:[0,1]
	v_pk_mul_f32 v[72:73], v[72:73], v[228:229] op_sel_hi:[1,0]
	v_pk_mul_f32 v[70:71], v[70:71], v[228:229] op_sel_hi:[1,0]
	v_pk_fma_f32 v[106:107], v[172:173], v[150:151], v[72:73] op_sel_hi:[1,0,1]
	v_pk_fma_f32 v[108:109], v[174:175], v[150:151], v[70:71] op_sel_hi:[1,0,1]
	v_mul_f32_e32 v71, v85, v107
	v_mul_f32_e32 v70, v83, v109
	v_pk_fma_f32 v[110:111], v[168:169], v[80:81], v[88:89] op_sel_hi:[1,0,1]
	v_pk_fma_f32 v[112:113], v[170:171], v[80:81], v[90:91] op_sel_hi:[1,0,1]
	v_fmac_f32_e32 v70, v82, v108
	v_fmac_f32_e32 v71, v84, v106
	v_mul_f32_e32 v88, v83, v113
	v_mul_f32_e32 v89, v85, v111
	v_add_f32_e32 v70, v70, v71
	v_fmac_f32_e32 v88, v82, v112
	v_fmac_f32_e32 v89, v84, v110
	v_add_f32_e32 v81, v70, v81
	ds_read_b128 v[70:73], v215 offset:9472
	ds_read_b128 v[82:85], v215 offset:13568
	v_add_f32_e32 v88, v88, v89
	v_add_f32_e32 v138, v93, v88
	s_waitcnt lgkmcnt(1)
	v_pk_mul_f32 v[88:89], v[86:87], v[72:73] op_sel_hi:[0,1]
	v_pk_mul_f32 v[92:93], v[86:87], v[70:71] op_sel_hi:[0,1]
	v_pk_fma_f32 v[90:91], v[178:179], v[78:79], v[88:89] op_sel_hi:[1,0,1]
	v_pk_fma_f32 v[92:93], v[180:181], v[78:79], v[92:93] op_sel_hi:[1,0,1]
	s_waitcnt lgkmcnt(0)
	v_mul_f32_e32 v89, v85, v91
	v_mul_f32_e32 v88, v83, v93
	v_fmac_f32_e32 v88, v82, v92
	v_fmac_f32_e32 v89, v84, v90
	v_add_f32_e32 v88, v88, v89
	v_add_f32_e32 v151, v87, v88
	v_pk_mul_f32 v[88:89], v[224:225], v[72:73] op_sel_hi:[0,1]
	v_pk_mul_f32 v[96:97], v[224:225], v[70:71] op_sel_hi:[0,1]
	v_pk_fma_f32 v[94:95], v[182:183], v[78:79], v[88:89] op_sel:[0,1,0]
	v_pk_fma_f32 v[96:97], v[184:185], v[78:79], v[96:97] op_sel:[0,1,0]
	v_mul_f32_e32 v88, v85, v95
	v_mul_f32_e32 v87, v83, v97
	v_fmac_f32_e32 v87, v82, v96
	v_fmac_f32_e32 v88, v84, v94
	v_add_f32_e32 v87, v87, v88
	v_pk_mul_f32 v[88:89], v[226:227], v[72:73] op_sel_hi:[0,1]
	v_pk_mul_f32 v[102:103], v[226:227], v[70:71] op_sel_hi:[0,1]
	v_pk_mul_f32 v[72:73], v[228:229], v[72:73] op_sel_hi:[0,1]
	v_pk_mul_f32 v[70:71], v[228:229], v[70:71] op_sel_hi:[0,1]
	v_add_f32_e32 v152, v98, v87
	v_pk_fma_f32 v[98:99], v[100:101], v[80:81], v[88:89] op_sel_hi:[1,0,1]
	v_pk_fma_f32 v[100:101], v[186:187], v[80:81], v[102:103] op_sel_hi:[1,0,1]
	v_pk_fma_f32 v[102:103], v[104:105], v[150:151], v[72:73] op_sel_hi:[1,0,1]
	v_pk_fma_f32 v[104:105], v[188:189], v[150:151], v[70:71] op_sel_hi:[1,0,1]
	v_mul_f32_e32 v87, v83, v101
	v_mul_f32_e32 v88, v85, v99
	v_mul_f32_e32 v70, v83, v105
	v_mul_f32_e32 v71, v85, v103
	v_fmac_f32_e32 v87, v82, v100
	v_fmac_f32_e32 v88, v84, v98
	v_fmac_f32_e32 v70, v82, v104
	v_fmac_f32_e32 v71, v84, v102
	v_add_f32_e32 v87, v87, v88
	v_add_f32_e32 v70, v70, v71
	v_add_f32_e32 v154, v138, v87
	v_add_f32_e32 v155, v81, v70
	ds_read_b128 v[70:73], v215 offset:9600
	ds_read_b128 v[138:141], v215 offset:13696
	s_waitcnt lgkmcnt(1)
	v_pk_mul_f32 v[82:83], v[86:87], v[72:73] op_sel_hi:[0,1]
	v_pk_mul_f32 v[84:85], v[86:87], v[70:71] op_sel_hi:[0,1]
	v_pk_fma_f32 v[86:87], v[190:191], v[78:79], v[82:83] op_sel_hi:[1,0,1]
	v_pk_fma_f32 v[88:89], v[192:193], v[78:79], v[84:85] op_sel_hi:[1,0,1]
	s_waitcnt lgkmcnt(0)
	v_mul_f32_e32 v82, v141, v87
	v_mul_f32_e32 v81, v139, v89
	v_fmac_f32_e32 v81, v138, v88
	v_fmac_f32_e32 v82, v140, v86
	v_add_f32_e32 v81, v81, v82
	v_pk_mul_f32 v[82:83], v[224:225], v[72:73] op_sel_hi:[0,1]
	v_pk_mul_f32 v[84:85], v[224:225], v[70:71] op_sel_hi:[0,1]
	v_pk_fma_f32 v[82:83], v[194:195], v[78:79], v[82:83] op_sel:[0,1,0]
	v_pk_fma_f32 v[84:85], v[74:75], v[78:79], v[84:85] op_sel:[0,1,0]
	v_mul_f32_e32 v75, v141, v83
	v_mul_f32_e32 v74, v139, v85
	v_fmac_f32_e32 v74, v138, v84
	v_fmac_f32_e32 v75, v140, v82
	v_add_f32_e32 v74, v74, v75
	v_add_f32_e32 v156, v152, v74
	v_pk_mul_f32 v[74:75], v[226:227], v[72:73] op_sel_hi:[0,1]
	v_pk_mul_f32 v[152:153], v[226:227], v[70:71] op_sel_hi:[0,1]
	v_add_f32_e32 v151, v151, v81
	v_pk_fma_f32 v[78:79], v[196:197], v[80:81], v[74:75] op_sel_hi:[1,0,1]
	v_pk_fma_f32 v[80:81], v[76:77], v[80:81], v[152:153] op_sel_hi:[1,0,1]
	v_mul_f32_e32 v75, v141, v79
	v_mul_f32_e32 v74, v139, v81
	v_fmac_f32_e32 v74, v138, v80
	v_fmac_f32_e32 v75, v140, v78
	v_add_f32_e32 v74, v74, v75
	v_pk_mul_f32 v[72:73], v[228:229], v[72:73] op_sel_hi:[0,1]
	v_pk_mul_f32 v[70:71], v[228:229], v[70:71] op_sel_hi:[0,1]
	v_add_f32_e32 v152, v154, v74
	v_pk_fma_f32 v[74:75], v[198:199], v[150:151], v[72:73] op_sel_hi:[1,0,1]
	v_pk_fma_f32 v[76:77], v[176:177], v[150:151], v[70:71] op_sel_hi:[1,0,1]
	v_mul_f32_e32 v71, v141, v75
	v_mul_f32_e32 v70, v139, v77
	v_fmac_f32_e32 v70, v138, v76
	v_fmac_f32_e32 v71, v140, v74
	v_add_f32_e32 v70, v70, v71
	s_nop 1
	v_add_f32_e32 v70, v155, v70
	s_waitcnt lgkmcnt(0)
	v_add_f32_dpp v71, v151, v151 quad_perm:[1,0,3,2] row_mask:0xf bank_mask:0xf
	s_nop 1
	s_waitcnt lgkmcnt(0)
	v_add_f32_dpp v71, v71, v71 quad_perm:[2,3,0,1] row_mask:0xf bank_mask:0xf
	s_nop 1
	s_waitcnt lgkmcnt(0)
	v_add_f32_dpp v71, v71, v71 row_half_mirror row_mask:0xf bank_mask:0xf
	v_cndmask_b32_e64 v177, v225, v71, s[50:51]
	s_nop 1
	s_waitcnt lgkmcnt(0)
	v_add_f32_dpp v71, v156, v156 quad_perm:[1,0,3,2] row_mask:0xf bank_mask:0xf
	s_nop 1
	s_waitcnt lgkmcnt(0)
	v_add_f32_dpp v71, v71, v71 quad_perm:[2,3,0,1] row_mask:0xf bank_mask:0xf
	s_nop 1
	s_waitcnt lgkmcnt(0)
	v_add_f32_dpp v71, v71, v71 row_half_mirror row_mask:0xf bank_mask:0xf
	v_cndmask_b32_e64 v176, v227, v71, s[50:51]
	s_nop 1
	s_waitcnt lgkmcnt(0)
	v_add_f32_dpp v71, v152, v152 quad_perm:[1,0,3,2] row_mask:0xf bank_mask:0xf
	s_nop 1
	s_waitcnt lgkmcnt(0)
	v_add_f32_dpp v71, v71, v71 quad_perm:[2,3,0,1] row_mask:0xf bank_mask:0xf
	s_nop 1
	s_waitcnt lgkmcnt(0)
	v_add_f32_dpp v71, v71, v71 row_half_mirror row_mask:0xf bank_mask:0xf
	v_cndmask_b32_e64 v175, v229, v71, s[50:51]
	s_nop 1
	s_waitcnt lgkmcnt(0)
	v_add_f32_dpp v70, v70, v70 quad_perm:[1,0,3,2] row_mask:0xf bank_mask:0xf
	s_nop 1
	s_waitcnt lgkmcnt(0)
	v_add_f32_dpp v70, v70, v70 quad_perm:[2,3,0,1] row_mask:0xf bank_mask:0xf
	s_nop 1
	s_waitcnt lgkmcnt(0)
	v_add_f32_dpp v70, v70, v70 row_half_mirror row_mask:0xf bank_mask:0xf
	v_cndmask_b32_e64 v174, v230, v70, s[50:51]
	ds_read_b128 v[70:73], v49 offset:16560
	ds_read2st64_b32 v[138:139], v201 offset0:12 offset1:13
	s_waitcnt lgkmcnt(1)
	v_mov_b32_e32 v166, v73
	s_waitcnt lgkmcnt(0)
	v_mul_f32_e32 v140, v66, v138
	v_mul_f32_e32 v138, v67, v139
	ds_read2st64_b32 v[66:67], v201 offset0:14 offset1:15
	ds_read_b128 v[150:153], v215 offset:9728
	ds_read_b128 v[154:157], v215 offset:13824
	ds_read_b128 v[162:165], v215 offset:9856
	ds_read_b128 v[168:171], v215 offset:13952
	s_waitcnt lgkmcnt(3)
	v_pk_mul_f32 v[158:159], v[140:141], v[152:153] op_sel_hi:[0,1]
	v_pk_mul_f32 v[160:161], v[140:141], v[150:151] op_sel_hi:[0,1]
	v_pk_fma_f32 v[122:123], v[122:123], v[70:71], v[158:159] op_sel_hi:[1,0,1]
	v_pk_fma_f32 v[124:125], v[124:125], v[70:71], v[160:161] op_sel_hi:[1,0,1]
	v_mul_f32_e32 v68, v68, v66
	v_mul_f32_e32 v66, v69, v67
	s_waitcnt lgkmcnt(2)
	v_mul_f32_e32 v67, v155, v125
	v_mul_f32_e32 v69, v157, v123
	v_pk_mul_f32 v[158:159], v[152:153], v[138:139] op_sel_hi:[1,0]
	v_pk_mul_f32 v[160:161], v[150:151], v[138:139] op_sel_hi:[1,0]
	v_fmac_f32_e32 v67, v154, v124
	v_fmac_f32_e32 v69, v156, v122
	v_pk_fma_f32 v[126:127], v[126:127], v[70:71], v[158:159] op_sel:[0,1,0]
	v_pk_fma_f32 v[128:129], v[128:129], v[70:71], v[160:161] op_sel:[0,1,0]
	v_add_f32_e32 v67, v67, v69
	v_mul_f32_e32 v69, v155, v129
	v_mul_f32_e32 v139, v157, v127
	v_fmac_f32_e32 v69, v154, v128
	v_fmac_f32_e32 v139, v156, v126
	v_add_f32_e32 v69, v69, v139
	v_add_f32_e32 v69, 0, v69
	v_pk_mul_f32 v[158:159], v[152:153], v[68:69] op_sel_hi:[1,0]
	v_pk_mul_f32 v[160:161], v[150:151], v[68:69] op_sel_hi:[1,0]
	v_add_f32_e32 v67, 0, v67
	v_pk_fma_f32 v[130:131], v[130:131], v[72:73], v[158:159] op_sel_hi:[1,0,1]
	v_pk_fma_f32 v[132:133], v[132:133], v[72:73], v[160:161] op_sel_hi:[1,0,1]
	v_mul_f32_e32 v141, v157, v131
	v_mul_f32_e32 v139, v155, v133
	v_pk_mul_f32 v[152:153], v[152:153], v[66:67] op_sel_hi:[1,0]
	v_fmac_f32_e32 v139, v154, v132
	v_fmac_f32_e32 v141, v156, v130
	v_pk_fma_f32 v[134:135], v[134:135], v[166:167], v[152:153] op_sel_hi:[1,0,1]
	v_add_f32_e32 v139, v139, v141
	v_mul_f32_e32 v141, v157, v135
	v_pk_mul_f32 v[150:151], v[150:151], v[66:67] op_sel_hi:[1,0]
	v_fmac_f32_e32 v141, v156, v134
	v_pk_fma_f32 v[136:137], v[136:137], v[166:167], v[150:151] op_sel_hi:[1,0,1]
	s_waitcnt lgkmcnt(1)
	v_pk_mul_f32 v[150:151], v[140:141], v[164:165] op_sel_hi:[0,1]
	v_pk_mul_f32 v[152:153], v[140:141], v[162:163] op_sel_hi:[0,1]
	v_pk_fma_f32 v[150:151], v[118:119], v[70:71], v[150:151] op_sel_hi:[1,0,1]
	v_pk_fma_f32 v[152:153], v[120:121], v[70:71], v[152:153] op_sel_hi:[1,0,1]
	s_waitcnt lgkmcnt(0)
	v_mul_f32_e32 v119, v171, v151
	v_mul_f32_e32 v118, v169, v153
	v_fmac_f32_e32 v118, v168, v152
	v_fmac_f32_e32 v119, v170, v150
	v_add_f32_e32 v139, 0, v139
	v_add_f32_e32 v118, v118, v119
	v_mul_f32_e32 v73, v155, v137
	v_add_f32_e32 v67, v67, v118
	v_pk_mul_f32 v[118:119], v[138:139], v[164:165] op_sel_hi:[0,1]
	v_pk_mul_f32 v[120:121], v[138:139], v[162:163] op_sel_hi:[0,1]
	v_fmac_f32_e32 v73, v154, v136
	v_pk_fma_f32 v[154:155], v[114:115], v[70:71], v[118:119] op_sel:[0,1,0]
	v_pk_fma_f32 v[156:157], v[116:117], v[70:71], v[120:121] op_sel:[0,1,0]
	v_mul_f32_e32 v115, v171, v155
	v_mul_f32_e32 v114, v169, v157
	v_fmac_f32_e32 v114, v168, v156
	v_fmac_f32_e32 v115, v170, v154
	v_add_f32_e32 v114, v114, v115
	v_add_f32_e32 v73, v73, v141
	v_add_f32_e32 v69, v69, v114
	v_add_f32_e32 v73, 0, v73
	v_pk_mul_f32 v[114:115], v[68:69], v[164:165] op_sel_hi:[0,1]
	v_pk_mul_f32 v[116:117], v[68:69], v[162:163] op_sel_hi:[0,1]
	v_pk_fma_f32 v[158:159], v[110:111], v[72:73], v[114:115] op_sel_hi:[1,0,1]
	v_pk_fma_f32 v[160:161], v[112:113], v[72:73], v[116:117] op_sel_hi:[1,0,1]
	v_mul_f32_e32 v111, v171, v159
	v_mul_f32_e32 v110, v169, v161
	v_fmac_f32_e32 v110, v168, v160
	v_fmac_f32_e32 v111, v170, v158
	v_add_f32_e32 v110, v110, v111
	v_add_f32_e32 v118, v139, v110
	v_pk_mul_f32 v[110:111], v[164:165], v[66:67] op_sel_hi:[1,0]
	v_pk_mul_f32 v[112:113], v[162:163], v[66:67] op_sel_hi:[1,0]
	v_pk_fma_f32 v[162:163], v[106:107], v[166:167], v[110:111] op_sel_hi:[1,0,1]
	v_pk_fma_f32 v[164:165], v[108:109], v[166:167], v[112:113] op_sel_hi:[1,0,1]
	v_mul_f32_e32 v107, v171, v163
	v_mul_f32_e32 v106, v169, v165
	v_fmac_f32_e32 v106, v168, v164
	v_fmac_f32_e32 v107, v170, v162
	v_add_f32_e32 v106, v106, v107
	v_add_f32_e32 v73, v106, v73
	ds_read_b128 v[106:109], v215 offset:9984
	ds_read_b128 v[110:113], v215 offset:14080
	s_waitcnt lgkmcnt(1)
	v_pk_mul_f32 v[114:115], v[140:141], v[108:109] op_sel_hi:[0,1]
	v_pk_mul_f32 v[116:117], v[140:141], v[106:107] op_sel_hi:[0,1]
	v_pk_fma_f32 v[90:91], v[90:91], v[70:71], v[114:115] op_sel_hi:[1,0,1]
	v_pk_fma_f32 v[92:93], v[92:93], v[70:71], v[116:117] op_sel_hi:[1,0,1]
	s_waitcnt lgkmcnt(0)
	v_mul_f32_e32 v115, v113, v91
	v_mul_f32_e32 v114, v111, v93
	v_fmac_f32_e32 v114, v110, v92
	v_fmac_f32_e32 v115, v112, v90
	v_add_f32_e32 v114, v114, v115
	v_add_f32_e32 v67, v67, v114
	v_pk_mul_f32 v[114:115], v[138:139], v[108:109] op_sel_hi:[0,1]
	v_pk_mul_f32 v[116:117], v[138:139], v[106:107] op_sel_hi:[0,1]
	v_pk_fma_f32 v[94:95], v[94:95], v[70:71], v[114:115] op_sel:[0,1,0]
	v_pk_fma_f32 v[96:97], v[96:97], v[70:71], v[116:117] op_sel:[0,1,0]
	v_mul_f32_e32 v115, v113, v95
	v_mul_f32_e32 v114, v111, v97
	v_fmac_f32_e32 v114, v110, v96
	v_fmac_f32_e32 v115, v112, v94
	v_add_f32_e32 v114, v114, v115
	v_add_f32_e32 v69, v69, v114
	v_pk_mul_f32 v[114:115], v[68:69], v[108:109] op_sel_hi:[0,1]
	v_pk_mul_f32 v[116:117], v[68:69], v[106:107] op_sel_hi:[0,1]
	v_pk_mul_f32 v[108:109], v[66:67], v[108:109] op_sel_hi:[0,1]
	v_pk_mul_f32 v[106:107], v[66:67], v[106:107] op_sel_hi:[0,1]
	v_pk_fma_f32 v[168:169], v[102:103], v[166:167], v[108:109] op_sel_hi:[1,0,1]
	v_pk_fma_f32 v[170:171], v[104:105], v[166:167], v[106:107] op_sel_hi:[1,0,1]
	v_pk_fma_f32 v[98:99], v[98:99], v[72:73], v[114:115] op_sel_hi:[1,0,1]
	v_pk_fma_f32 v[100:101], v[100:101], v[72:73], v[116:117] op_sel_hi:[1,0,1]
	v_mul_f32_e32 v102, v111, v171
	v_mul_f32_e32 v103, v113, v169
	v_mul_f32_e32 v114, v111, v101
	v_mul_f32_e32 v115, v113, v99
	v_fmac_f32_e32 v102, v110, v170
	v_fmac_f32_e32 v103, v112, v168
	v_fmac_f32_e32 v114, v110, v100
	v_fmac_f32_e32 v115, v112, v98
	v_add_f32_e32 v102, v102, v103
	v_add_f32_e32 v114, v114, v115
	v_add_f32_e32 v115, v73, v102
	ds_read_b128 v[102:105], v215 offset:10112
	ds_read_b128 v[106:109], v215 offset:14208
	v_add_f32_e32 v114, v118, v114
	s_waitcnt lgkmcnt(1)
	v_pk_mul_f32 v[110:111], v[140:141], v[104:105] op_sel_hi:[0,1]
	v_pk_mul_f32 v[112:113], v[140:141], v[102:103] op_sel_hi:[0,1]
	v_pk_fma_f32 v[140:141], v[86:87], v[70:71], v[110:111] op_sel_hi:[1,0,1]
	v_pk_fma_f32 v[172:173], v[88:89], v[70:71], v[112:113] op_sel_hi:[1,0,1]
	s_waitcnt lgkmcnt(0)
	v_mul_f32_e32 v86, v109, v141
	v_mul_f32_e32 v73, v107, v173
	v_fmac_f32_e32 v73, v106, v172
	v_fmac_f32_e32 v86, v108, v140
	v_add_f32_e32 v73, v73, v86
	v_pk_mul_f32 v[86:87], v[138:139], v[104:105] op_sel_hi:[0,1]
	v_pk_mul_f32 v[88:89], v[138:139], v[102:103] op_sel_hi:[0,1]
	v_pk_fma_f32 v[138:139], v[82:83], v[70:71], v[86:87] op_sel:[0,1,0]
	v_pk_fma_f32 v[70:71], v[84:85], v[70:71], v[88:89] op_sel:[0,1,0]
	v_add_f32_e32 v110, v67, v73
	v_mul_f32_e32 v67, v107, v71
	v_mul_f32_e32 v73, v109, v139
	v_fmac_f32_e32 v67, v106, v70
	v_fmac_f32_e32 v73, v108, v138
	v_add_f32_e32 v67, v67, v73
	v_pk_mul_f32 v[82:83], v[68:69], v[104:105] op_sel_hi:[0,1]
	v_pk_mul_f32 v[84:85], v[68:69], v[102:103] op_sel_hi:[0,1]
	v_add_f32_e32 v86, v69, v67
	v_pk_fma_f32 v[68:69], v[78:79], v[72:73], v[82:83] op_sel_hi:[1,0,1]
	v_pk_fma_f32 v[72:73], v[80:81], v[72:73], v[84:85] op_sel_hi:[1,0,1]
	v_mul_f32_e32 v78, v109, v69
	v_mul_f32_e32 v67, v107, v73
	v_fmac_f32_e32 v67, v106, v72
	v_fmac_f32_e32 v78, v108, v68
	v_add_f32_e32 v67, v67, v78
	v_pk_mul_f32 v[78:79], v[66:67], v[104:105] op_sel_hi:[0,1]
	v_pk_mul_f32 v[80:81], v[66:67], v[102:103] op_sel_hi:[0,1]
	v_add_f32_e32 v82, v114, v67
	v_pk_fma_f32 v[66:67], v[74:75], v[166:167], v[78:79] op_sel_hi:[1,0,1]
	v_pk_fma_f32 v[166:167], v[76:77], v[166:167], v[80:81] op_sel_hi:[1,0,1]
	v_mul_f32_e32 v75, v109, v67
	v_mul_f32_e32 v74, v107, v167
	v_fmac_f32_e32 v74, v106, v166
	v_fmac_f32_e32 v75, v108, v66
	v_add_f32_e32 v74, v74, v75
	s_nop 1
	v_add_f32_e32 v74, v115, v74
	s_waitcnt lgkmcnt(0)
	v_add_f32_dpp v75, v110, v110 quad_perm:[1,0,3,2] row_mask:0xf bank_mask:0xf
	s_nop 1
	s_waitcnt lgkmcnt(0)
	v_add_f32_dpp v75, v75, v75 quad_perm:[2,3,0,1] row_mask:0xf bank_mask:0xf
	s_nop 1
	s_waitcnt lgkmcnt(0)
	v_add_f32_dpp v75, v75, v75 row_half_mirror row_mask:0xf bank_mask:0xf
	v_cndmask_b32_e64 v179, v177, v75, s[52:53]
	s_nop 1
	s_waitcnt lgkmcnt(0)
	v_add_f32_dpp v75, v86, v86 quad_perm:[1,0,3,2] row_mask:0xf bank_mask:0xf
	s_nop 1
	s_waitcnt lgkmcnt(0)
	v_add_f32_dpp v75, v75, v75 quad_perm:[2,3,0,1] row_mask:0xf bank_mask:0xf
	s_nop 1
	s_waitcnt lgkmcnt(0)
	v_add_f32_dpp v75, v75, v75 row_half_mirror row_mask:0xf bank_mask:0xf
	v_cndmask_b32_e64 v181, v176, v75, s[52:53]
	s_nop 1
	s_waitcnt lgkmcnt(0)
	v_add_f32_dpp v75, v82, v82 quad_perm:[1,0,3,2] row_mask:0xf bank_mask:0xf
	s_nop 1
	s_waitcnt lgkmcnt(0)
	v_add_f32_dpp v75, v75, v75 quad_perm:[2,3,0,1] row_mask:0xf bank_mask:0xf
	s_nop 1
	s_waitcnt lgkmcnt(0)
	v_add_f32_dpp v75, v75, v75 row_half_mirror row_mask:0xf bank_mask:0xf
	v_cndmask_b32_e64 v183, v175, v75, s[52:53]
	s_nop 1
	s_waitcnt lgkmcnt(0)
	v_add_f32_dpp v74, v74, v74 quad_perm:[1,0,3,2] row_mask:0xf bank_mask:0xf
	s_nop 1
	s_waitcnt lgkmcnt(0)
	v_add_f32_dpp v74, v74, v74 quad_perm:[2,3,0,1] row_mask:0xf bank_mask:0xf
	s_nop 1
	s_waitcnt lgkmcnt(0)
	v_add_f32_dpp v74, v74, v74 row_half_mirror row_mask:0xf bank_mask:0xf
	v_cndmask_b32_e64 v185, v174, v74, s[52:53]
	ds_read_b128 v[74:77], v49 offset:16448
	ds_read_b128 v[174:177], v49 offset:16576
	ds_read2st64_b32 v[78:79], v201 offset0:16 offset1:17
	s_waitcnt lgkmcnt(1)
	v_mov_b32_e32 v184, v177
	s_waitcnt lgkmcnt(0)
	v_mul_f32_e32 v82, v74, v78
	v_mul_f32_e32 v178, v75, v79
	ds_read2st64_b32 v[74:75], v201 offset0:18 offset1:19
	s_waitcnt lgkmcnt(0)
	v_mul_f32_e32 v180, v76, v74
	v_mul_f32_e32 v182, v77, v75
	ds_read_b128 v[74:77], v215 offset:10240
	ds_read_b128 v[78:81], v215 offset:14336
	s_waitcnt lgkmcnt(1)
	v_pk_mul_f32 v[84:85], v[82:83], v[76:77] op_sel_hi:[0,1]
	v_pk_mul_f32 v[86:87], v[82:83], v[74:75] op_sel_hi:[0,1]
	v_pk_fma_f32 v[118:119], v[122:123], v[174:175], v[84:85] op_sel_hi:[1,0,1]
	v_pk_fma_f32 v[120:121], v[124:125], v[174:175], v[86:87] op_sel_hi:[1,0,1]
	s_waitcnt lgkmcnt(0)
	v_mul_f32_e32 v84, v81, v119
	v_mul_f32_e32 v83, v79, v121
	v_fmac_f32_e32 v83, v78, v120
	v_fmac_f32_e32 v84, v80, v118
	v_add_f32_e32 v83, v83, v84
	v_pk_mul_f32 v[84:85], v[76:77], v[178:179] op_sel_hi:[1,0]
	v_pk_mul_f32 v[86:87], v[74:75], v[178:179] op_sel_hi:[1,0]
	v_pk_fma_f32 v[122:123], v[126:127], v[174:175], v[84:85] op_sel:[0,1,0]
	v_pk_fma_f32 v[124:125], v[128:129], v[174:175], v[86:87] op_sel:[0,1,0]
	v_mul_f32_e32 v85, v81, v123
	v_mul_f32_e32 v84, v79, v125
	v_fmac_f32_e32 v84, v78, v124
	v_fmac_f32_e32 v85, v80, v122
	v_add_f32_e32 v84, v84, v85
	v_add_f32_e32 v88, 0, v84
	v_pk_mul_f32 v[84:85], v[76:77], v[180:181] op_sel_hi:[1,0]
	v_pk_mul_f32 v[86:87], v[74:75], v[180:181] op_sel_hi:[1,0]
	v_pk_mul_f32 v[76:77], v[76:77], v[182:183] op_sel_hi:[1,0]
	v_pk_mul_f32 v[74:75], v[74:75], v[182:183] op_sel_hi:[1,0]
	v_pk_fma_f32 v[126:127], v[130:131], v[176:177], v[84:85] op_sel_hi:[1,0,1]
	v_pk_fma_f32 v[128:129], v[132:133], v[176:177], v[86:87] op_sel_hi:[1,0,1]
	v_pk_fma_f32 v[130:131], v[134:135], v[184:185], v[76:77] op_sel_hi:[1,0,1]
	v_pk_fma_f32 v[132:133], v[136:137], v[184:185], v[74:75] op_sel_hi:[1,0,1]
	v_mul_f32_e32 v75, v81, v131
	v_mul_f32_e32 v74, v79, v133
	v_fmac_f32_e32 v74, v78, v132
	v_fmac_f32_e32 v75, v80, v130
	v_mul_f32_e32 v84, v79, v129
	v_mul_f32_e32 v85, v81, v127
	v_add_f32_e32 v74, v74, v75
	v_fmac_f32_e32 v84, v78, v128
	v_fmac_f32_e32 v85, v80, v126
	v_add_f32_e32 v134, 0, v74
	ds_read_b128 v[74:77], v215 offset:10368
	ds_read_b128 v[78:81], v215 offset:14464
	v_add_f32_e32 v83, 0, v83
	v_add_f32_e32 v84, v84, v85
	v_add_f32_e32 v89, 0, v84
	s_waitcnt lgkmcnt(1)
	v_pk_mul_f32 v[84:85], v[82:83], v[76:77] op_sel_hi:[0,1]
	v_pk_mul_f32 v[86:87], v[82:83], v[74:75] op_sel_hi:[0,1]
	v_pk_fma_f32 v[114:115], v[150:151], v[174:175], v[84:85] op_sel_hi:[1,0,1]
	v_pk_fma_f32 v[116:117], v[152:153], v[174:175], v[86:87] op_sel_hi:[1,0,1]
	s_waitcnt lgkmcnt(0)
	v_mul_f32_e32 v85, v81, v115
	v_mul_f32_e32 v84, v79, v117
	v_fmac_f32_e32 v84, v78, v116
	v_fmac_f32_e32 v85, v80, v114
	v_add_f32_e32 v84, v84, v85
	v_add_f32_e32 v83, v83, v84
	v_pk_mul_f32 v[84:85], v[178:179], v[76:77] op_sel_hi:[0,1]
	v_pk_mul_f32 v[86:87], v[178:179], v[74:75] op_sel_hi:[0,1]
	v_pk_fma_f32 v[110:111], v[154:155], v[174:175], v[84:85] op_sel:[0,1,0]
	v_pk_fma_f32 v[112:113], v[156:157], v[174:175], v[86:87] op_sel:[0,1,0]
	v_mul_f32_e32 v85, v81, v111
	v_mul_f32_e32 v84, v79, v113
	v_fmac_f32_e32 v84, v78, v112
	v_fmac_f32_e32 v85, v80, v110
	v_add_f32_e32 v84, v84, v85
	v_add_f32_e32 v135, v88, v84
	v_pk_mul_f32 v[84:85], v[180:181], v[76:77] op_sel_hi:[0,1]
	v_pk_mul_f32 v[86:87], v[180:181], v[74:75] op_sel_hi:[0,1]
	v_pk_mul_f32 v[76:77], v[76:77], v[182:183] op_sel_hi:[1,0]
	v_pk_mul_f32 v[74:75], v[74:75], v[182:183] op_sel_hi:[1,0]
	v_pk_fma_f32 v[102:103], v[162:163], v[184:185], v[76:77] op_sel_hi:[1,0,1]
	v_pk_fma_f32 v[104:105], v[164:165], v[184:185], v[74:75] op_sel_hi:[1,0,1]
	v_mul_f32_e32 v75, v81, v103
	v_mul_f32_e32 v74, v79, v105
	v_pk_fma_f32 v[106:107], v[158:159], v[176:177], v[84:85] op_sel_hi:[1,0,1]
	v_pk_fma_f32 v[108:109], v[160:161], v[176:177], v[86:87] op_sel_hi:[1,0,1]
	v_fmac_f32_e32 v74, v78, v104
	v_fmac_f32_e32 v75, v80, v102
	v_mul_f32_e32 v84, v79, v109
	v_mul_f32_e32 v85, v81, v107
	v_add_f32_e32 v74, v74, v75
	v_fmac_f32_e32 v84, v78, v108
	v_fmac_f32_e32 v85, v80, v106
	v_add_f32_e32 v134, v74, v134
	ds_read_b128 v[74:77], v215 offset:10496
	ds_read_b128 v[78:81], v215 offset:14592
	v_add_f32_e32 v84, v84, v85
	v_add_f32_e32 v136, v89, v84
	s_waitcnt lgkmcnt(1)
	v_pk_mul_f32 v[84:85], v[82:83], v[76:77] op_sel_hi:[0,1]
	v_pk_mul_f32 v[88:89], v[82:83], v[74:75] op_sel_hi:[0,1]
	v_pk_fma_f32 v[86:87], v[90:91], v[174:175], v[84:85] op_sel_hi:[1,0,1]
	v_pk_fma_f32 v[88:89], v[92:93], v[174:175], v[88:89] op_sel_hi:[1,0,1]
	s_waitcnt lgkmcnt(0)
	v_mul_f32_e32 v85, v81, v87
	v_mul_f32_e32 v84, v79, v89
	v_fmac_f32_e32 v84, v78, v88
	v_fmac_f32_e32 v85, v80, v86
	v_add_f32_e32 v84, v84, v85
	v_add_f32_e32 v154, v83, v84
	v_pk_mul_f32 v[84:85], v[178:179], v[76:77] op_sel_hi:[0,1]
	v_pk_mul_f32 v[92:93], v[178:179], v[74:75] op_sel_hi:[0,1]
	v_pk_fma_f32 v[90:91], v[94:95], v[174:175], v[84:85] op_sel:[0,1,0]
	v_pk_fma_f32 v[92:93], v[96:97], v[174:175], v[92:93] op_sel:[0,1,0]
	v_mul_f32_e32 v84, v81, v91
	v_mul_f32_e32 v83, v79, v93
	v_fmac_f32_e32 v83, v78, v92
	v_fmac_f32_e32 v84, v80, v90
	v_add_f32_e32 v83, v83, v84
	v_pk_mul_f32 v[84:85], v[180:181], v[76:77] op_sel_hi:[0,1]
	v_pk_mul_f32 v[96:97], v[180:181], v[74:75] op_sel_hi:[0,1]
	v_pk_mul_f32 v[76:77], v[182:183], v[76:77] op_sel_hi:[0,1]
	v_pk_mul_f32 v[74:75], v[182:183], v[74:75] op_sel_hi:[0,1]
	v_pk_fma_f32 v[94:95], v[98:99], v[176:177], v[84:85] op_sel_hi:[1,0,1]
	v_pk_fma_f32 v[96:97], v[100:101], v[176:177], v[96:97] op_sel_hi:[1,0,1]
	v_pk_fma_f32 v[98:99], v[168:169], v[184:185], v[76:77] op_sel_hi:[1,0,1]
	v_pk_fma_f32 v[100:101], v[170:171], v[184:185], v[74:75] op_sel_hi:[1,0,1]
	v_add_f32_e32 v155, v135, v83
	v_mul_f32_e32 v83, v79, v97
	v_mul_f32_e32 v84, v81, v95
	v_mul_f32_e32 v74, v79, v101
	v_mul_f32_e32 v75, v81, v99
	v_fmac_f32_e32 v83, v78, v96
	v_fmac_f32_e32 v84, v80, v94
	v_fmac_f32_e32 v74, v78, v100
	v_fmac_f32_e32 v75, v80, v98
	v_add_f32_e32 v83, v83, v84
	v_add_f32_e32 v74, v74, v75
	v_add_f32_e32 v156, v136, v83
	v_add_f32_e32 v157, v134, v74
	ds_read_b128 v[134:137], v215 offset:10624
	ds_read_b128 v[150:153], v215 offset:14720
	s_waitcnt lgkmcnt(1)
	v_pk_mul_f32 v[74:75], v[82:83], v[136:137] op_sel_hi:[0,1]
	v_pk_mul_f32 v[76:77], v[82:83], v[134:135] op_sel_hi:[0,1]
	v_pk_fma_f32 v[82:83], v[140:141], v[174:175], v[74:75] op_sel_hi:[1,0,1]
	v_pk_fma_f32 v[84:85], v[172:173], v[174:175], v[76:77] op_sel_hi:[1,0,1]
	s_waitcnt lgkmcnt(0)
	v_mul_f32_e32 v75, v153, v83
	v_mul_f32_e32 v74, v151, v85
	v_fmac_f32_e32 v74, v150, v84
	v_fmac_f32_e32 v75, v152, v82
	v_add_f32_e32 v74, v74, v75
	v_add_f32_e32 v140, v154, v74
	v_pk_mul_f32 v[74:75], v[178:179], v[136:137] op_sel_hi:[0,1]
	v_pk_mul_f32 v[76:77], v[178:179], v[134:135] op_sel_hi:[0,1]
	v_pk_fma_f32 v[78:79], v[138:139], v[174:175], v[74:75] op_sel:[0,1,0]
	v_pk_fma_f32 v[80:81], v[70:71], v[174:175], v[76:77] op_sel:[0,1,0]
	v_mul_f32_e32 v71, v153, v79
	v_mul_f32_e32 v70, v151, v81
	v_fmac_f32_e32 v70, v150, v80
	v_fmac_f32_e32 v71, v152, v78
	v_add_f32_e32 v70, v70, v71
	v_add_f32_e32 v138, v155, v70
	v_pk_mul_f32 v[70:71], v[180:181], v[136:137] op_sel_hi:[0,1]
	v_pk_mul_f32 v[76:77], v[180:181], v[134:135] op_sel_hi:[0,1]
	v_pk_fma_f32 v[74:75], v[68:69], v[176:177], v[70:71] op_sel_hi:[1,0,1]
	v_pk_fma_f32 v[76:77], v[72:73], v[176:177], v[76:77] op_sel_hi:[1,0,1]
	v_mul_f32_e32 v69, v153, v75
	v_mul_f32_e32 v68, v151, v77
	v_fmac_f32_e32 v68, v150, v76
	v_fmac_f32_e32 v69, v152, v74
	v_add_f32_e32 v68, v68, v69
	v_add_f32_e32 v154, v156, v68
	v_pk_mul_f32 v[68:69], v[182:183], v[136:137] op_sel_hi:[0,1]
	v_pk_mul_f32 v[72:73], v[182:183], v[134:135] op_sel_hi:[0,1]
	v_pk_fma_f32 v[70:71], v[66:67], v[184:185], v[68:69] op_sel_hi:[1,0,1]
	v_pk_fma_f32 v[72:73], v[166:167], v[184:185], v[72:73] op_sel_hi:[1,0,1]
	v_mul_f32_e32 v67, v153, v71
	v_mul_f32_e32 v66, v151, v73
	v_fmac_f32_e32 v66, v150, v72
	v_fmac_f32_e32 v67, v152, v70
	v_add_f32_e32 v66, v66, v67
	s_nop 1
	v_add_f32_e32 v66, v157, v66
	s_waitcnt lgkmcnt(0)
	v_add_f32_dpp v67, v140, v140 quad_perm:[1,0,3,2] row_mask:0xf bank_mask:0xf
	s_nop 1
	s_waitcnt lgkmcnt(0)
	v_add_f32_dpp v67, v67, v67 quad_perm:[2,3,0,1] row_mask:0xf bank_mask:0xf
	s_nop 1
	s_waitcnt lgkmcnt(0)
	v_add_f32_dpp v67, v67, v67 row_half_mirror row_mask:0xf bank_mask:0xf
	v_cndmask_b32_e64 v141, v179, v67, s[54:55]
	s_nop 1
	s_waitcnt lgkmcnt(0)
	v_add_f32_dpp v67, v138, v138 quad_perm:[1,0,3,2] row_mask:0xf bank_mask:0xf
	s_nop 1
	s_waitcnt lgkmcnt(0)
	v_add_f32_dpp v67, v67, v67 quad_perm:[2,3,0,1] row_mask:0xf bank_mask:0xf
	s_nop 1
	s_waitcnt lgkmcnt(0)
	v_add_f32_dpp v67, v67, v67 row_half_mirror row_mask:0xf bank_mask:0xf
	v_cndmask_b32_e64 v139, v181, v67, s[54:55]
	s_nop 1
	s_waitcnt lgkmcnt(0)
	v_add_f32_dpp v67, v154, v154 quad_perm:[1,0,3,2] row_mask:0xf bank_mask:0xf
	s_nop 1
	s_waitcnt lgkmcnt(0)
	v_add_f32_dpp v67, v67, v67 quad_perm:[2,3,0,1] row_mask:0xf bank_mask:0xf
	s_nop 1
	s_waitcnt lgkmcnt(0)
	v_add_f32_dpp v67, v67, v67 row_half_mirror row_mask:0xf bank_mask:0xf
	v_cndmask_b32_e64 v137, v183, v67, s[54:55]
	s_nop 1
	s_waitcnt lgkmcnt(0)
	v_add_f32_dpp v66, v66, v66 quad_perm:[1,0,3,2] row_mask:0xf bank_mask:0xf
	s_nop 1
	s_waitcnt lgkmcnt(0)
	v_add_f32_dpp v66, v66, v66 quad_perm:[2,3,0,1] row_mask:0xf bank_mask:0xf
	s_nop 1
	s_waitcnt lgkmcnt(0)
	v_add_f32_dpp v66, v66, v66 row_half_mirror row_mask:0xf bank_mask:0xf
	v_cndmask_b32_e64 v135, v185, v66, s[54:55]
	ds_read_b128 v[150:153], v49 offset:16464
	ds_read_b128 v[66:69], v49 offset:16592
	ds_read2st64_b32 v[154:155], v201 offset0:20 offset1:21
	s_waitcnt lgkmcnt(0)
	v_mul_f32_e32 v140, v150, v154
	v_mul_f32_e32 v136, v151, v155
	ds_read2st64_b32 v[150:151], v201 offset0:22 offset1:23
	s_waitcnt lgkmcnt(0)
	v_mul_f32_e32 v138, v152, v150
	v_mul_f32_e32 v134, v153, v151
	ds_read_b128 v[150:153], v215 offset:10752
	ds_read_b128 v[154:157], v215 offset:14848
	s_waitcnt lgkmcnt(1)
	v_pk_mul_f32 v[158:159], v[140:141], v[152:153] op_sel_hi:[0,1]
	v_pk_mul_f32 v[160:161], v[140:141], v[150:151] op_sel_hi:[0,1]
	v_pk_fma_f32 v[118:119], v[118:119], v[66:67], v[158:159] op_sel_hi:[1,0,1]
	v_pk_fma_f32 v[120:121], v[120:121], v[66:67], v[160:161] op_sel_hi:[1,0,1]
	s_waitcnt lgkmcnt(0)
	v_mul_f32_e32 v159, v157, v119
	v_mul_f32_e32 v158, v155, v121
	v_fmac_f32_e32 v158, v154, v120
	v_fmac_f32_e32 v159, v156, v118
	v_add_f32_e32 v158, v158, v159
	v_add_f32_e32 v164, 0, v158
	v_pk_mul_f32 v[158:159], v[152:153], v[136:137] op_sel_hi:[1,0]
	v_pk_mul_f32 v[160:161], v[150:151], v[136:137] op_sel_hi:[1,0]
	v_pk_fma_f32 v[122:123], v[122:123], v[66:67], v[158:159] op_sel:[0,1,0]
	v_pk_fma_f32 v[124:125], v[124:125], v[66:67], v[160:161] op_sel:[0,1,0]
	v_mul_f32_e32 v159, v157, v123
	v_mul_f32_e32 v158, v155, v125
	v_fmac_f32_e32 v158, v154, v124
	v_fmac_f32_e32 v159, v156, v122
	v_add_f32_e32 v158, v158, v159
	v_add_f32_e32 v165, 0, v158
	v_pk_mul_f32 v[158:159], v[152:153], v[138:139] op_sel_hi:[1,0]
	v_pk_mul_f32 v[160:161], v[150:151], v[138:139] op_sel_hi:[1,0]
	v_pk_fma_f32 v[126:127], v[126:127], v[68:69], v[158:159] op_sel_hi:[1,0,1]
	v_pk_fma_f32 v[128:129], v[128:129], v[68:69], v[160:161] op_sel_hi:[1,0,1]
	v_mul_f32_e32 v159, v157, v127
	v_mul_f32_e32 v158, v155, v129
	v_fmac_f32_e32 v158, v154, v128
	v_fmac_f32_e32 v159, v156, v126
	v_add_f32_e32 v158, v158, v159
	v_add_f32_e32 v166, 0, v158
	v_pk_mul_f32 v[152:153], v[152:153], v[134:135] op_sel_hi:[1,0]
	v_pk_mul_f32 v[158:159], v[150:151], v[134:135] op_sel_hi:[1,0]
	v_mov_b32_e32 v150, v69
	v_pk_fma_f32 v[130:131], v[130:131], v[150:151], v[152:153] op_sel_hi:[1,0,1]
	v_pk_fma_f32 v[132:133], v[132:133], v[150:151], v[158:159] op_sel_hi:[1,0,1]
	v_mul_f32_e32 v151, v157, v131
	v_mul_f32_e32 v69, v155, v133
	v_fmac_f32_e32 v69, v154, v132
	v_fmac_f32_e32 v151, v156, v130
	ds_read_b128 v[152:155], v215 offset:10880
	ds_read_b128 v[156:159], v215 offset:14976
	v_add_f32_e32 v69, v69, v151
	v_add_f32_e32 v69, 0, v69
	s_waitcnt lgkmcnt(1)
	v_pk_mul_f32 v[160:161], v[140:141], v[154:155] op_sel_hi:[0,1]
	v_pk_mul_f32 v[162:163], v[140:141], v[152:153] op_sel_hi:[0,1]
	v_pk_fma_f32 v[114:115], v[114:115], v[66:67], v[160:161] op_sel_hi:[1,0,1]
	v_pk_fma_f32 v[116:117], v[116:117], v[66:67], v[162:163] op_sel_hi:[1,0,1]
	s_waitcnt lgkmcnt(0)
	v_mul_f32_e32 v160, v159, v115
	v_mul_f32_e32 v151, v157, v117
	v_fmac_f32_e32 v151, v156, v116
	v_fmac_f32_e32 v160, v158, v114
	v_add_f32_e32 v151, v151, v160
	v_pk_mul_f32 v[160:161], v[136:137], v[154:155] op_sel_hi:[0,1]
	v_pk_mul_f32 v[162:163], v[136:137], v[152:153] op_sel_hi:[0,1]
	v_pk_fma_f32 v[110:111], v[110:111], v[66:67], v[160:161] op_sel:[0,1,0]
	v_pk_fma_f32 v[112:113], v[112:113], v[66:67], v[162:163] op_sel:[0,1,0]
	v_mul_f32_e32 v161, v159, v111
	v_mul_f32_e32 v160, v157, v113
	v_fmac_f32_e32 v160, v156, v112
	v_fmac_f32_e32 v161, v158, v110
	v_add_f32_e32 v160, v160, v161
	v_add_f32_e32 v172, v165, v160
	v_pk_mul_f32 v[160:161], v[138:139], v[154:155] op_sel_hi:[0,1]
	v_pk_mul_f32 v[162:163], v[138:139], v[152:153] op_sel_hi:[0,1]
	v_pk_fma_f32 v[106:107], v[106:107], v[68:69], v[160:161] op_sel_hi:[1,0,1]
	v_pk_fma_f32 v[108:109], v[108:109], v[68:69], v[162:163] op_sel_hi:[1,0,1]
	v_mul_f32_e32 v161, v159, v107
	v_mul_f32_e32 v160, v157, v109
	v_fmac_f32_e32 v160, v156, v108
	v_fmac_f32_e32 v161, v158, v106
	v_add_f32_e32 v151, v164, v151
	v_add_f32_e32 v160, v160, v161
	v_pk_mul_f32 v[154:155], v[154:155], v[134:135] op_sel_hi:[1,0]
	v_pk_mul_f32 v[152:153], v[152:153], v[134:135] op_sel_hi:[1,0]
	v_add_f32_e32 v173, v166, v160
	v_pk_fma_f32 v[102:103], v[102:103], v[150:151], v[154:155] op_sel_hi:[1,0,1]
	v_pk_fma_f32 v[104:105], v[104:105], v[150:151], v[152:153] op_sel_hi:[1,0,1]
	ds_read_b128 v[164:167], v215 offset:11008
	ds_read_b128 v[168:171], v215 offset:15104
	v_mul_f32_e32 v152, v157, v105
	v_mul_f32_e32 v153, v159, v103
	v_fmac_f32_e32 v152, v156, v104
	v_fmac_f32_e32 v153, v158, v102
	v_add_f32_e32 v152, v152, v153
	v_add_f32_e32 v69, v152, v69
	s_waitcnt lgkmcnt(1)
	v_pk_mul_f32 v[152:153], v[140:141], v[166:167] op_sel_hi:[0,1]
	v_pk_mul_f32 v[154:155], v[140:141], v[164:165] op_sel_hi:[0,1]
	v_pk_fma_f32 v[152:153], v[86:87], v[66:67], v[152:153] op_sel_hi:[1,0,1]
	v_pk_fma_f32 v[154:155], v[88:89], v[66:67], v[154:155] op_sel_hi:[1,0,1]
	s_waitcnt lgkmcnt(0)
	v_mul_f32_e32 v87, v171, v153
	v_mul_f32_e32 v86, v169, v155
	v_fmac_f32_e32 v86, v168, v154
	v_fmac_f32_e32 v87, v170, v152
	v_add_f32_e32 v86, v86, v87
	v_add_f32_e32 v151, v151, v86
	v_pk_mul_f32 v[86:87], v[136:137], v[166:167] op_sel_hi:[0,1]
	v_pk_mul_f32 v[88:89], v[136:137], v[164:165] op_sel_hi:[0,1]
	v_pk_fma_f32 v[156:157], v[90:91], v[66:67], v[86:87] op_sel:[0,1,0]
	v_pk_fma_f32 v[158:159], v[92:93], v[66:67], v[88:89] op_sel:[0,1,0]
	v_mul_f32_e32 v87, v171, v157
	v_mul_f32_e32 v86, v169, v159
	v_fmac_f32_e32 v86, v168, v158
	v_fmac_f32_e32 v87, v170, v156
	v_add_f32_e32 v86, v86, v87
	v_add_f32_e32 v172, v172, v86
	v_pk_mul_f32 v[86:87], v[138:139], v[166:167] op_sel_hi:[0,1]
	v_pk_mul_f32 v[88:89], v[138:139], v[164:165] op_sel_hi:[0,1]
	v_pk_fma_f32 v[160:161], v[94:95], v[68:69], v[86:87] op_sel_hi:[1,0,1]
	v_pk_fma_f32 v[162:163], v[96:97], v[68:69], v[88:89] op_sel_hi:[1,0,1]
	v_mul_f32_e32 v87, v171, v161
	v_mul_f32_e32 v86, v169, v163
	v_fmac_f32_e32 v86, v168, v162
	v_fmac_f32_e32 v87, v170, v160
	v_add_f32_e32 v86, v86, v87
	v_add_f32_e32 v173, v173, v86
	v_pk_mul_f32 v[86:87], v[134:135], v[166:167] op_sel_hi:[0,1]
	v_pk_mul_f32 v[88:89], v[134:135], v[164:165] op_sel_hi:[0,1]
	v_pk_fma_f32 v[98:99], v[98:99], v[150:151], v[86:87] op_sel_hi:[1,0,1]
	v_pk_fma_f32 v[100:101], v[100:101], v[150:151], v[88:89] op_sel_hi:[1,0,1]
	v_mul_f32_e32 v87, v171, v99
	v_mul_f32_e32 v86, v169, v101
	v_fmac_f32_e32 v86, v168, v100
	v_fmac_f32_e32 v87, v170, v98
	v_add_f32_e32 v86, v86, v87
	v_add_f32_e32 v174, v69, v86
	ds_read_b128 v[86:89], v215 offset:11136
	ds_read_b128 v[90:93], v215 offset:15232
	s_waitcnt lgkmcnt(1)
	v_pk_mul_f32 v[94:95], v[140:141], v[88:89] op_sel_hi:[0,1]
	v_pk_mul_f32 v[96:97], v[140:141], v[86:87] op_sel_hi:[0,1]
	v_pk_fma_f32 v[82:83], v[82:83], v[66:67], v[94:95] op_sel_hi:[1,0,1]
	v_pk_fma_f32 v[84:85], v[84:85], v[66:67], v[96:97] op_sel_hi:[1,0,1]
	s_waitcnt lgkmcnt(0)
	v_mul_f32_e32 v94, v93, v83
	v_mul_f32_e32 v69, v91, v85
	v_fmac_f32_e32 v69, v90, v84
	v_fmac_f32_e32 v94, v92, v82
	v_add_f32_e32 v69, v69, v94
	v_pk_mul_f32 v[94:95], v[136:137], v[88:89] op_sel_hi:[0,1]
	v_pk_mul_f32 v[96:97], v[136:137], v[86:87] op_sel_hi:[0,1]
	v_pk_fma_f32 v[78:79], v[78:79], v[66:67], v[94:95] op_sel:[0,1,0]
	v_pk_fma_f32 v[80:81], v[80:81], v[66:67], v[96:97] op_sel:[0,1,0]
	v_mul_f32_e32 v67, v93, v79
	v_mul_f32_e32 v66, v91, v81
	v_fmac_f32_e32 v66, v90, v80
	v_fmac_f32_e32 v67, v92, v78
	v_add_f32_e32 v66, v66, v67
	v_add_f32_e32 v96, v172, v66
	v_pk_mul_f32 v[66:67], v[138:139], v[88:89] op_sel_hi:[0,1]
	v_pk_mul_f32 v[94:95], v[138:139], v[86:87] op_sel_hi:[0,1]
	v_pk_fma_f32 v[164:165], v[74:75], v[68:69], v[66:67] op_sel_hi:[1,0,1]
	v_pk_fma_f32 v[166:167], v[76:77], v[68:69], v[94:95] op_sel_hi:[1,0,1]
	v_mul_f32_e32 v67, v93, v165
	v_mul_f32_e32 v66, v91, v167
	v_fmac_f32_e32 v66, v90, v166
	v_fmac_f32_e32 v67, v92, v164
	v_add_f32_e32 v66, v66, v67
	v_add_f32_e32 v140, v151, v69
	v_add_f32_e32 v74, v173, v66
	v_pk_mul_f32 v[66:67], v[134:135], v[88:89] op_sel_hi:[0,1]
	v_pk_mul_f32 v[68:69], v[134:135], v[86:87] op_sel_hi:[0,1]
	v_pk_fma_f32 v[168:169], v[70:71], v[150:151], v[66:67] op_sel_hi:[1,0,1]
	v_pk_fma_f32 v[170:171], v[72:73], v[150:151], v[68:69] op_sel_hi:[1,0,1]
	v_mul_f32_e32 v67, v93, v169
	v_mul_f32_e32 v66, v91, v171
	v_fmac_f32_e32 v66, v90, v170
	v_fmac_f32_e32 v67, v92, v168
	v_add_f32_e32 v66, v66, v67
	s_nop 1
	v_add_f32_e32 v66, v174, v66
	s_waitcnt lgkmcnt(0)
	v_add_f32_dpp v67, v140, v140 quad_perm:[1,0,3,2] row_mask:0xf bank_mask:0xf
	s_nop 1
	s_waitcnt lgkmcnt(0)
	v_add_f32_dpp v67, v67, v67 quad_perm:[2,3,0,1] row_mask:0xf bank_mask:0xf
	s_nop 1
	s_waitcnt lgkmcnt(0)
	v_add_f32_dpp v67, v67, v67 row_half_mirror row_mask:0xf bank_mask:0xf
	v_cndmask_b32_e64 v177, v141, v67, s[56:57]
	s_nop 1
	s_waitcnt lgkmcnt(0)
	v_add_f32_dpp v67, v96, v96 quad_perm:[1,0,3,2] row_mask:0xf bank_mask:0xf
	s_nop 1
	s_waitcnt lgkmcnt(0)
	v_add_f32_dpp v67, v67, v67 quad_perm:[2,3,0,1] row_mask:0xf bank_mask:0xf
	s_nop 1
	s_waitcnt lgkmcnt(0)
	v_add_f32_dpp v67, v67, v67 row_half_mirror row_mask:0xf bank_mask:0xf
	v_cndmask_b32_e64 v179, v139, v67, s[56:57]
	s_nop 1
	s_waitcnt lgkmcnt(0)
	v_add_f32_dpp v67, v74, v74 quad_perm:[1,0,3,2] row_mask:0xf bank_mask:0xf
	s_nop 1
	s_waitcnt lgkmcnt(0)
	v_add_f32_dpp v67, v67, v67 quad_perm:[2,3,0,1] row_mask:0xf bank_mask:0xf
	s_nop 1
	s_waitcnt lgkmcnt(0)
	v_add_f32_dpp v67, v67, v67 row_half_mirror row_mask:0xf bank_mask:0xf
	v_cndmask_b32_e64 v181, v137, v67, s[56:57]
	s_nop 1
	s_waitcnt lgkmcnt(0)
	v_add_f32_dpp v66, v66, v66 quad_perm:[1,0,3,2] row_mask:0xf bank_mask:0xf
	s_nop 1
	s_waitcnt lgkmcnt(0)
	v_add_f32_dpp v66, v66, v66 quad_perm:[2,3,0,1] row_mask:0xf bank_mask:0xf
	s_nop 1
	s_waitcnt lgkmcnt(0)
	v_add_f32_dpp v66, v66, v66 row_half_mirror row_mask:0xf bank_mask:0xf
	v_cndmask_b32_e64 v182, v135, v66, s[56:57]
	ds_read_b128 v[66:69], v49 offset:16480
	ds_read_b128 v[172:175], v49 offset:16608
	ds_read2st64_b32 v[70:71], v201 offset0:24 offset1:25
	s_waitcnt lgkmcnt(1)
	v_mov_b32_e32 v180, v175
	s_waitcnt lgkmcnt(0)
	v_mul_f32_e32 v138, v66, v70
	v_mul_f32_e32 v150, v67, v71
	ds_read2st64_b32 v[66:67], v201 offset0:26 offset1:27
	ds_read_b128 v[86:89], v215 offset:11264
	ds_read_b128 v[90:93], v215 offset:15360
	s_waitcnt lgkmcnt(2)
	v_mul_f32_e32 v176, v68, v66
	v_mul_f32_e32 v178, v69, v67
	s_waitcnt lgkmcnt(1)
	v_pk_mul_f32 v[66:67], v[138:139], v[88:89] op_sel_hi:[0,1]
	v_pk_mul_f32 v[68:69], v[138:139], v[86:87] op_sel_hi:[0,1]
	v_pk_fma_f32 v[66:67], v[118:119], v[172:173], v[66:67] op_sel_hi:[1,0,1]
	v_pk_fma_f32 v[68:69], v[120:121], v[172:173], v[68:69] op_sel_hi:[1,0,1]
	s_waitcnt lgkmcnt(0)
	v_mul_f32_e32 v71, v93, v67
	v_mul_f32_e32 v70, v91, v69
	v_fmac_f32_e32 v70, v90, v68
	v_fmac_f32_e32 v71, v92, v66
	v_add_f32_e32 v70, v70, v71
	v_add_f32_e32 v96, 0, v70
	v_pk_mul_f32 v[70:71], v[88:89], v[150:151] op_sel_hi:[1,0]
	v_pk_mul_f32 v[72:73], v[86:87], v[150:151] op_sel_hi:[1,0]
	v_pk_fma_f32 v[70:71], v[122:123], v[172:173], v[70:71] op_sel:[0,1,0]
	v_pk_fma_f32 v[72:73], v[124:125], v[172:173], v[72:73] op_sel:[0,1,0]
	v_mul_f32_e32 v75, v93, v71
	v_mul_f32_e32 v74, v91, v73
	v_fmac_f32_e32 v74, v90, v72
	v_fmac_f32_e32 v75, v92, v70
	v_add_f32_e32 v74, v74, v75
	v_add_f32_e32 v134, 0, v74
	v_pk_mul_f32 v[74:75], v[88:89], v[176:177] op_sel_hi:[1,0]
	v_pk_mul_f32 v[76:77], v[86:87], v[176:177] op_sel_hi:[1,0]
	v_pk_fma_f32 v[74:75], v[126:127], v[174:175], v[74:75] op_sel_hi:[1,0,1]
	v_pk_fma_f32 v[76:77], v[128:129], v[174:175], v[76:77] op_sel_hi:[1,0,1]
	v_mul_f32_e32 v95, v93, v75
	v_mul_f32_e32 v94, v91, v77
	v_fmac_f32_e32 v94, v90, v76
	v_fmac_f32_e32 v95, v92, v74
	v_add_f32_e32 v94, v94, v95
	v_add_f32_e32 v126, 0, v94
	v_pk_mul_f32 v[88:89], v[88:89], v[178:179] op_sel_hi:[1,0]
	v_pk_mul_f32 v[94:95], v[86:87], v[178:179] op_sel_hi:[1,0]
	v_pk_fma_f32 v[86:87], v[130:131], v[180:181], v[88:89] op_sel_hi:[1,0,1]
	v_pk_fma_f32 v[88:89], v[132:133], v[180:181], v[94:95] op_sel_hi:[1,0,1]
	ds_read_b128 v[118:121], v215 offset:11392
	ds_read_b128 v[122:125], v215 offset:15488
	v_mul_f32_e32 v91, v91, v89
	v_fmac_f32_e32 v91, v90, v88
	v_mul_f32_e32 v90, v93, v87
	v_fmac_f32_e32 v90, v92, v86
	v_add_f32_e32 v90, v91, v90
	v_add_f32_e32 v127, 0, v90
	s_waitcnt lgkmcnt(1)
	v_pk_mul_f32 v[90:91], v[138:139], v[120:121] op_sel_hi:[0,1]
	v_pk_mul_f32 v[92:93], v[138:139], v[118:119] op_sel_hi:[0,1]
	v_pk_fma_f32 v[90:91], v[114:115], v[172:173], v[90:91] op_sel_hi:[1,0,1]
	v_pk_fma_f32 v[92:93], v[116:117], v[172:173], v[92:93] op_sel_hi:[1,0,1]
	s_waitcnt lgkmcnt(0)
	v_mul_f32_e32 v95, v125, v91
	v_mul_f32_e32 v94, v123, v93
	v_fmac_f32_e32 v94, v122, v92
	v_fmac_f32_e32 v95, v124, v90
	v_add_f32_e32 v94, v94, v95
	v_add_f32_e32 v128, v96, v94
	v_pk_mul_f32 v[94:95], v[150:151], v[120:121] op_sel_hi:[0,1]
	v_pk_mul_f32 v[96:97], v[150:151], v[118:119] op_sel_hi:[0,1]
	v_pk_fma_f32 v[94:95], v[110:111], v[172:173], v[94:95] op_sel:[0,1,0]
	v_pk_fma_f32 v[96:97], v[112:113], v[172:173], v[96:97] op_sel:[0,1,0]
	v_mul_f32_e32 v111, v125, v95
	v_mul_f32_e32 v110, v123, v97
	v_fmac_f32_e32 v110, v122, v96
	v_fmac_f32_e32 v111, v124, v94
	v_add_f32_e32 v110, v110, v111
	v_add_f32_e32 v130, v134, v110
	v_pk_mul_f32 v[110:111], v[176:177], v[120:121] op_sel_hi:[0,1]
	v_pk_mul_f32 v[112:113], v[176:177], v[118:119] op_sel_hi:[0,1]
	v_pk_fma_f32 v[114:115], v[106:107], v[174:175], v[110:111] op_sel_hi:[1,0,1]
	v_pk_fma_f32 v[116:117], v[108:109], v[174:175], v[112:113] op_sel_hi:[1,0,1]
	v_mul_f32_e32 v107, v125, v115
	v_mul_f32_e32 v106, v123, v117
	v_fmac_f32_e32 v106, v122, v116
	v_fmac_f32_e32 v107, v124, v114
	v_add_f32_e32 v106, v106, v107
	v_add_f32_e32 v134, v126, v106
	v_pk_mul_f32 v[106:107], v[120:121], v[178:179] op_sel_hi:[1,0]
	v_pk_mul_f32 v[108:109], v[118:119], v[178:179] op_sel_hi:[1,0]
	v_pk_fma_f32 v[118:119], v[102:103], v[180:181], v[106:107] op_sel_hi:[1,0,1]
	v_pk_fma_f32 v[120:121], v[104:105], v[180:181], v[108:109] op_sel_hi:[1,0,1]
	v_mul_f32_e32 v103, v125, v119
	v_mul_f32_e32 v102, v123, v121
	v_fmac_f32_e32 v102, v122, v120
	v_fmac_f32_e32 v103, v124, v118
	v_add_f32_e32 v102, v102, v103
	v_add_f32_e32 v139, v102, v127
	ds_read_b128 v[102:105], v215 offset:11520
	ds_read_b128 v[106:109], v215 offset:15616
	s_waitcnt lgkmcnt(1)
	v_pk_mul_f32 v[110:111], v[138:139], v[104:105] op_sel_hi:[0,1]
	v_pk_mul_f32 v[112:113], v[138:139], v[102:103] op_sel_hi:[0,1]
	v_pk_fma_f32 v[122:123], v[152:153], v[172:173], v[110:111] op_sel_hi:[1,0,1]
	v_pk_fma_f32 v[124:125], v[154:155], v[172:173], v[112:113] op_sel_hi:[1,0,1]
	s_waitcnt lgkmcnt(0)
	v_mul_f32_e32 v111, v109, v123
	v_mul_f32_e32 v110, v107, v125
	v_fmac_f32_e32 v110, v106, v124
	v_fmac_f32_e32 v111, v108, v122
	v_add_f32_e32 v110, v110, v111
	v_add_f32_e32 v151, v128, v110
	v_pk_mul_f32 v[110:111], v[150:151], v[104:105] op_sel_hi:[0,1]
	v_pk_mul_f32 v[112:113], v[150:151], v[102:103] op_sel_hi:[0,1]
	v_pk_fma_f32 v[126:127], v[156:157], v[172:173], v[110:111] op_sel:[0,1,0]
	v_pk_fma_f32 v[128:129], v[158:159], v[172:173], v[112:113] op_sel:[0,1,0]
	v_mul_f32_e32 v111, v109, v127
	v_mul_f32_e32 v110, v107, v129
	v_fmac_f32_e32 v110, v106, v128
	v_fmac_f32_e32 v111, v108, v126
	v_add_f32_e32 v110, v110, v111
	v_add_f32_e32 v154, v130, v110
	v_pk_mul_f32 v[110:111], v[176:177], v[104:105] op_sel_hi:[0,1]
	v_pk_mul_f32 v[112:113], v[176:177], v[102:103] op_sel_hi:[0,1]
	v_pk_fma_f32 v[130:131], v[160:161], v[174:175], v[110:111] op_sel_hi:[1,0,1]
	v_pk_fma_f32 v[132:133], v[162:163], v[174:175], v[112:113] op_sel_hi:[1,0,1]
	v_mul_f32_e32 v111, v109, v131
	v_mul_f32_e32 v110, v107, v133
	v_fmac_f32_e32 v110, v106, v132
	v_fmac_f32_e32 v111, v108, v130
	v_add_f32_e32 v110, v110, v111
	v_pk_mul_f32 v[104:105], v[178:179], v[104:105] op_sel_hi:[0,1]
	v_pk_mul_f32 v[102:103], v[178:179], v[102:103] op_sel_hi:[0,1]
	v_add_f32_e32 v110, v134, v110
	v_pk_fma_f32 v[134:135], v[98:99], v[180:181], v[104:105] op_sel_hi:[1,0,1]
	v_pk_fma_f32 v[136:137], v[100:101], v[180:181], v[102:103] op_sel_hi:[1,0,1]
	v_mul_f32_e32 v99, v109, v135
	v_mul_f32_e32 v98, v107, v137
	v_fmac_f32_e32 v98, v106, v136
	v_fmac_f32_e32 v99, v108, v134
	v_add_f32_e32 v98, v98, v99
	v_add_f32_e32 v111, v139, v98
	ds_read_b128 v[98:101], v215 offset:11648
	ds_read_b128 v[102:105], v215 offset:15744
	s_waitcnt lgkmcnt(1)
	v_pk_mul_f32 v[106:107], v[138:139], v[100:101] op_sel_hi:[0,1]
	v_pk_mul_f32 v[108:109], v[138:139], v[98:99] op_sel_hi:[0,1]
	v_pk_fma_f32 v[138:139], v[82:83], v[172:173], v[106:107] op_sel_hi:[1,0,1]
	v_pk_fma_f32 v[140:141], v[84:85], v[172:173], v[108:109] op_sel_hi:[1,0,1]
	s_waitcnt lgkmcnt(0)
	v_mul_f32_e32 v83, v105, v139
	v_mul_f32_e32 v82, v103, v141
	v_fmac_f32_e32 v82, v102, v140
	v_fmac_f32_e32 v83, v104, v138
	v_add_f32_e32 v82, v82, v83
	v_add_f32_e32 v106, v151, v82
	v_pk_mul_f32 v[82:83], v[150:151], v[100:101] op_sel_hi:[0,1]
	v_pk_mul_f32 v[84:85], v[150:151], v[98:99] op_sel_hi:[0,1]
	v_pk_fma_f32 v[150:151], v[78:79], v[172:173], v[82:83] op_sel:[0,1,0]
	v_pk_fma_f32 v[152:153], v[80:81], v[172:173], v[84:85] op_sel:[0,1,0]
	v_mul_f32_e32 v79, v105, v151
	v_mul_f32_e32 v78, v103, v153
	v_fmac_f32_e32 v78, v102, v152
	v_fmac_f32_e32 v79, v104, v150
	v_add_f32_e32 v78, v78, v79
	v_add_f32_e32 v82, v154, v78
	v_pk_mul_f32 v[78:79], v[176:177], v[100:101] op_sel_hi:[0,1]
	v_pk_mul_f32 v[80:81], v[176:177], v[98:99] op_sel_hi:[0,1]
	v_pk_fma_f32 v[154:155], v[164:165], v[174:175], v[78:79] op_sel_hi:[1,0,1]
	v_pk_fma_f32 v[156:157], v[166:167], v[174:175], v[80:81] op_sel_hi:[1,0,1]
	v_mul_f32_e32 v79, v105, v155
	v_mul_f32_e32 v78, v103, v157
	v_fmac_f32_e32 v78, v102, v156
	v_fmac_f32_e32 v79, v104, v154
	v_add_f32_e32 v78, v78, v79
	v_add_f32_e32 v83, v110, v78
	v_pk_mul_f32 v[78:79], v[178:179], v[100:101] op_sel_hi:[0,1]
	v_pk_mul_f32 v[80:81], v[178:179], v[98:99] op_sel_hi:[0,1]
	v_pk_fma_f32 v[158:159], v[168:169], v[180:181], v[78:79] op_sel_hi:[1,0,1]
	v_pk_fma_f32 v[160:161], v[170:171], v[180:181], v[80:81] op_sel_hi:[1,0,1]
	v_mul_f32_e32 v79, v105, v159
	v_mul_f32_e32 v78, v103, v161
	v_fmac_f32_e32 v78, v102, v160
	v_fmac_f32_e32 v79, v104, v158
	v_add_f32_e32 v78, v78, v79
	s_nop 1
	v_add_f32_e32 v78, v111, v78
	s_waitcnt lgkmcnt(0)
	v_add_f32_dpp v79, v106, v106 quad_perm:[1,0,3,2] row_mask:0xf bank_mask:0xf
	s_nop 1
	s_waitcnt lgkmcnt(0)
	v_add_f32_dpp v79, v79, v79 quad_perm:[2,3,0,1] row_mask:0xf bank_mask:0xf
	s_nop 1
	s_waitcnt lgkmcnt(0)
	v_add_f32_dpp v79, v79, v79 row_half_mirror row_mask:0xf bank_mask:0xf
	v_cndmask_b32_e64 v163, v177, v79, s[58:59]
	s_nop 1
	s_waitcnt lgkmcnt(0)
	v_add_f32_dpp v79, v82, v82 quad_perm:[1,0,3,2] row_mask:0xf bank_mask:0xf
	s_nop 1
	s_waitcnt lgkmcnt(0)
	v_add_f32_dpp v79, v79, v79 quad_perm:[2,3,0,1] row_mask:0xf bank_mask:0xf
	s_nop 1
	s_waitcnt lgkmcnt(0)
	v_add_f32_dpp v79, v79, v79 row_half_mirror row_mask:0xf bank_mask:0xf
	v_cndmask_b32_e64 v165, v179, v79, s[58:59]
	s_nop 1
	s_waitcnt lgkmcnt(0)
	v_add_f32_dpp v79, v83, v83 quad_perm:[1,0,3,2] row_mask:0xf bank_mask:0xf
	s_nop 1
	s_waitcnt lgkmcnt(0)
	v_add_f32_dpp v79, v79, v79 quad_perm:[2,3,0,1] row_mask:0xf bank_mask:0xf
	s_nop 1
	s_waitcnt lgkmcnt(0)
	v_add_f32_dpp v79, v79, v79 row_half_mirror row_mask:0xf bank_mask:0xf
	v_cndmask_b32_e64 v167, v181, v79, s[58:59]
	s_nop 1
	s_waitcnt lgkmcnt(0)
	v_add_f32_dpp v78, v78, v78 quad_perm:[1,0,3,2] row_mask:0xf bank_mask:0xf
	s_nop 1
	s_waitcnt lgkmcnt(0)
	v_add_f32_dpp v78, v78, v78 quad_perm:[2,3,0,1] row_mask:0xf bank_mask:0xf
	s_nop 1
	s_waitcnt lgkmcnt(0)
	v_add_f32_dpp v78, v78, v78 row_half_mirror row_mask:0xf bank_mask:0xf
	v_cndmask_b32_e64 v169, v182, v78, s[58:59]
	ds_read_b128 v[82:85], v49 offset:16496
	ds_read_b128 v[78:81], v49 offset:16624
	ds_read2st64_b32 v[98:99], v201 offset0:28 offset1:29
	s_waitcnt lgkmcnt(1)
	v_mov_b32_e32 v170, v81
	s_waitcnt lgkmcnt(0)
	v_mul_f32_e32 v168, v82, v98
	v_mul_f32_e32 v166, v83, v99
	ds_read2st64_b32 v[82:83], v201 offset0:30 offset1:31
	ds_read_b128 v[106:109], v215 offset:11776
	ds_read_b128 v[110:113], v215 offset:15872
	s_waitcnt lgkmcnt(2)
	v_mul_f32_e32 v164, v84, v82
	v_mul_f32_e32 v162, v85, v83
	s_waitcnt lgkmcnt(1)
	v_pk_mul_f32 v[82:83], v[168:169], v[108:109] op_sel_hi:[0,1]
	v_pk_mul_f32 v[84:85], v[168:169], v[106:107] op_sel_hi:[0,1]
	v_pk_fma_f32 v[104:105], v[66:67], v[78:79], v[82:83] op_sel_hi:[1,0,1]
	v_pk_fma_f32 v[102:103], v[68:69], v[78:79], v[84:85] op_sel_hi:[1,0,1]
	s_waitcnt lgkmcnt(0)
	v_mul_f32_e32 v67, v113, v105
	v_mul_f32_e32 v66, v111, v103
	v_fmac_f32_e32 v66, v110, v102
	v_fmac_f32_e32 v67, v112, v104
	v_add_f32_e32 v66, v66, v67
	v_add_f32_e32 v171, 0, v66
	v_pk_mul_f32 v[66:67], v[108:109], v[166:167] op_sel_hi:[1,0]
	v_pk_mul_f32 v[68:69], v[106:107], v[166:167] op_sel_hi:[1,0]
	v_pk_fma_f32 v[100:101], v[70:71], v[78:79], v[66:67] op_sel:[0,1,0]
	v_pk_fma_f32 v[98:99], v[72:73], v[78:79], v[68:69] op_sel:[0,1,0]
	v_mul_f32_e32 v67, v113, v101
	v_mul_f32_e32 v66, v111, v99
	v_fmac_f32_e32 v66, v110, v98
	v_fmac_f32_e32 v67, v112, v100
	v_add_f32_e32 v66, v66, v67
	v_add_f32_e32 v172, 0, v66
	v_pk_mul_f32 v[66:67], v[108:109], v[164:165] op_sel_hi:[1,0]
	v_pk_mul_f32 v[68:69], v[106:107], v[164:165] op_sel_hi:[1,0]
	v_pk_fma_f32 v[84:85], v[74:75], v[80:81], v[66:67] op_sel_hi:[1,0,1]
	v_pk_fma_f32 v[82:83], v[76:77], v[80:81], v[68:69] op_sel_hi:[1,0,1]
	v_mul_f32_e32 v67, v113, v85
	v_mul_f32_e32 v66, v111, v83
	v_fmac_f32_e32 v66, v110, v82
	v_fmac_f32_e32 v67, v112, v84
	v_add_f32_e32 v66, v66, v67
	v_add_f32_e32 v173, 0, v66
	v_pk_mul_f32 v[66:67], v[108:109], v[162:163] op_sel_hi:[1,0]
	v_pk_mul_f32 v[70:71], v[106:107], v[162:163] op_sel_hi:[1,0]
	v_pk_fma_f32 v[68:69], v[86:87], v[170:171], v[66:67] op_sel_hi:[1,0,1]
	v_pk_fma_f32 v[66:67], v[88:89], v[170:171], v[70:71] op_sel_hi:[1,0,1]
	v_mul_f32_e32 v71, v113, v69
	v_mul_f32_e32 v70, v111, v67
	v_fmac_f32_e32 v70, v110, v66
	v_fmac_f32_e32 v71, v112, v68
	v_add_f32_e32 v70, v70, v71
	v_add_f32_e32 v174, 0, v70
	ds_read_b128 v[70:73], v215 offset:11904
	ds_read_b128 v[74:77], v215 offset:16000
	s_waitcnt lgkmcnt(1)
	v_pk_mul_f32 v[86:87], v[168:169], v[72:73] op_sel_hi:[0,1]
	v_pk_mul_f32 v[88:89], v[168:169], v[70:71] op_sel_hi:[0,1]
	v_pk_fma_f32 v[112:113], v[90:91], v[78:79], v[86:87] op_sel_hi:[1,0,1]
	v_pk_fma_f32 v[110:111], v[92:93], v[78:79], v[88:89] op_sel_hi:[1,0,1]
	s_waitcnt lgkmcnt(0)
	v_mul_f32_e32 v87, v77, v113
	v_mul_f32_e32 v86, v75, v111
	v_fmac_f32_e32 v86, v74, v110
	v_fmac_f32_e32 v87, v76, v112
	v_add_f32_e32 v86, v86, v87
	v_add_f32_e32 v171, v171, v86
	v_pk_mul_f32 v[86:87], v[166:167], v[72:73] op_sel_hi:[0,1]
	v_pk_mul_f32 v[88:89], v[166:167], v[70:71] op_sel_hi:[0,1]
	v_pk_fma_f32 v[108:109], v[94:95], v[78:79], v[86:87] op_sel:[0,1,0]
	v_pk_fma_f32 v[106:107], v[96:97], v[78:79], v[88:89] op_sel:[0,1,0]
	v_mul_f32_e32 v87, v77, v109
	v_mul_f32_e32 v86, v75, v107
	v_fmac_f32_e32 v86, v74, v106
	v_fmac_f32_e32 v87, v76, v108
	v_add_f32_e32 v86, v86, v87
	v_add_f32_e32 v172, v172, v86
	v_pk_mul_f32 v[86:87], v[164:165], v[72:73] op_sel_hi:[0,1]
	v_pk_mul_f32 v[90:91], v[164:165], v[70:71] op_sel_hi:[0,1]
	v_pk_mul_f32 v[70:71], v[70:71], v[162:163] op_sel_hi:[1,0]
	v_pk_fma_f32 v[88:89], v[114:115], v[80:81], v[86:87] op_sel_hi:[1,0,1]
	v_pk_fma_f32 v[86:87], v[116:117], v[80:81], v[90:91] op_sel_hi:[1,0,1]
	v_pk_mul_f32 v[72:73], v[72:73], v[162:163] op_sel_hi:[1,0]
	v_pk_fma_f32 v[70:71], v[120:121], v[170:171], v[70:71] op_sel_hi:[1,0,1]
	v_mul_f32_e32 v90, v75, v87
	v_pk_fma_f32 v[72:73], v[118:119], v[170:171], v[72:73] op_sel_hi:[1,0,1]
	v_mul_f32_e32 v75, v75, v71
	v_fmac_f32_e32 v90, v74, v86
	v_fmac_f32_e32 v75, v74, v70
	v_mul_f32_e32 v74, v77, v73
	v_fmac_f32_e32 v74, v76, v72
	v_mul_f32_e32 v91, v77, v89
	v_add_f32_e32 v74, v75, v74
	v_fmac_f32_e32 v91, v76, v88
	v_add_f32_e32 v174, v74, v174
	ds_read_b128 v[74:77], v215 offset:12032
	ds_read_b128 v[94:97], v215 offset:16128
	v_add_f32_e32 v90, v90, v91
	v_add_f32_e32 v173, v173, v90
	s_waitcnt lgkmcnt(1)
	v_pk_mul_f32 v[90:91], v[168:169], v[76:77] op_sel_hi:[0,1]
	v_pk_mul_f32 v[92:93], v[168:169], v[74:75] op_sel_hi:[0,1]
	v_pk_fma_f32 v[120:121], v[122:123], v[78:79], v[90:91] op_sel_hi:[1,0,1]
	v_pk_fma_f32 v[118:119], v[124:125], v[78:79], v[92:93] op_sel_hi:[1,0,1]
	s_waitcnt lgkmcnt(0)
	v_mul_f32_e32 v91, v97, v121
	v_mul_f32_e32 v90, v95, v119
	v_fmac_f32_e32 v90, v94, v118
	v_fmac_f32_e32 v91, v96, v120
	v_add_f32_e32 v90, v90, v91
	v_add_f32_e32 v124, v171, v90
	v_pk_mul_f32 v[90:91], v[166:167], v[76:77] op_sel_hi:[0,1]
	v_pk_mul_f32 v[92:93], v[166:167], v[74:75] op_sel_hi:[0,1]
	v_pk_fma_f32 v[116:117], v[126:127], v[78:79], v[90:91] op_sel:[0,1,0]
	v_pk_fma_f32 v[114:115], v[128:129], v[78:79], v[92:93] op_sel:[0,1,0]
	v_mul_f32_e32 v91, v97, v117
	v_mul_f32_e32 v90, v95, v115
	v_fmac_f32_e32 v90, v94, v114
	v_fmac_f32_e32 v91, v96, v116
	v_add_f32_e32 v90, v90, v91
	v_add_f32_e32 v171, v172, v90
	v_pk_mul_f32 v[90:91], v[164:165], v[76:77] op_sel_hi:[0,1]
	v_pk_mul_f32 v[122:123], v[164:165], v[74:75] op_sel_hi:[0,1]
	v_pk_mul_f32 v[74:75], v[162:163], v[74:75] op_sel_hi:[0,1]
	v_pk_fma_f32 v[92:93], v[130:131], v[80:81], v[90:91] op_sel_hi:[1,0,1]
	v_pk_fma_f32 v[90:91], v[132:133], v[80:81], v[122:123] op_sel_hi:[1,0,1]
	v_pk_mul_f32 v[76:77], v[162:163], v[76:77] op_sel_hi:[0,1]
	v_pk_fma_f32 v[74:75], v[136:137], v[170:171], v[74:75] op_sel_hi:[1,0,1]
	v_mul_f32_e32 v122, v95, v91
	v_pk_fma_f32 v[76:77], v[134:135], v[170:171], v[76:77] op_sel_hi:[1,0,1]
	v_mul_f32_e32 v95, v95, v75
	ds_read_b128 v[130:133], v215 offset:12160
	ds_read_b128 v[134:137], v215 offset:16256
	v_fmac_f32_e32 v122, v94, v90
	v_mul_f32_e32 v123, v97, v93
	v_fmac_f32_e32 v95, v94, v74
	v_mul_f32_e32 v94, v97, v77
	v_fmac_f32_e32 v123, v96, v92
	v_fmac_f32_e32 v94, v96, v76
	v_add_f32_e32 v122, v122, v123
	v_add_f32_e32 v94, v95, v94
	v_add_f32_e32 v172, v173, v122
	v_add_f32_e32 v173, v174, v94
	s_waitcnt lgkmcnt(1)
	v_pk_mul_f32 v[94:95], v[168:169], v[132:133] op_sel_hi:[0,1]
	v_pk_mul_f32 v[96:97], v[168:169], v[130:131] op_sel_hi:[0,1]
	v_pk_fma_f32 v[128:129], v[138:139], v[78:79], v[94:95] op_sel_hi:[1,0,1]
	v_pk_fma_f32 v[126:127], v[140:141], v[78:79], v[96:97] op_sel_hi:[1,0,1]
	s_waitcnt lgkmcnt(0)
	v_mul_f32_e32 v95, v137, v129
	v_mul_f32_e32 v94, v135, v127
	v_fmac_f32_e32 v94, v134, v126
	v_fmac_f32_e32 v95, v136, v128
	v_add_f32_e32 v94, v94, v95
	v_add_f32_e32 v138, v124, v94
	v_pk_mul_f32 v[94:95], v[166:167], v[132:133] op_sel_hi:[0,1]
	v_pk_mul_f32 v[96:97], v[166:167], v[130:131] op_sel_hi:[0,1]
	v_pk_fma_f32 v[124:125], v[150:151], v[78:79], v[94:95] op_sel:[0,1,0]
	v_pk_fma_f32 v[122:123], v[152:153], v[78:79], v[96:97] op_sel:[0,1,0]
	v_mul_f32_e32 v79, v137, v125
	v_mul_f32_e32 v78, v135, v123
	v_fmac_f32_e32 v78, v134, v122
	v_fmac_f32_e32 v79, v136, v124
	v_add_f32_e32 v78, v78, v79
	v_add_f32_e32 v139, v171, v78
	v_pk_mul_f32 v[78:79], v[164:165], v[132:133] op_sel_hi:[0,1]
	v_pk_mul_f32 v[94:95], v[164:165], v[130:131] op_sel_hi:[0,1]
	v_pk_fma_f32 v[96:97], v[154:155], v[80:81], v[78:79] op_sel_hi:[1,0,1]
	v_pk_fma_f32 v[94:95], v[156:157], v[80:81], v[94:95] op_sel_hi:[1,0,1]
	v_mul_f32_e32 v79, v137, v97
	v_mul_f32_e32 v78, v135, v95
	v_fmac_f32_e32 v78, v134, v94
	v_fmac_f32_e32 v79, v136, v96
	v_add_f32_e32 v78, v78, v79
	v_add_f32_e32 v141, v172, v78
	v_pk_mul_f32 v[78:79], v[162:163], v[132:133] op_sel_hi:[0,1]
	v_pk_mul_f32 v[130:131], v[162:163], v[130:131] op_sel_hi:[0,1]
	v_pk_fma_f32 v[80:81], v[158:159], v[170:171], v[78:79] op_sel_hi:[1,0,1]
	v_pk_fma_f32 v[78:79], v[160:161], v[170:171], v[130:131] op_sel_hi:[1,0,1]
	v_mul_f32_e32 v131, v137, v81
	v_mul_f32_e32 v130, v135, v79
	v_fmac_f32_e32 v130, v134, v78
	v_fmac_f32_e32 v131, v136, v80
	v_add_f32_e32 v130, v130, v131
	s_nop 1
	v_add_f32_e32 v130, v173, v130
	ds_read2st64_b32 v[136:137], v220 offset1:1
	s_waitcnt lgkmcnt(1)
	v_add_f32_dpp v131, v138, v138 quad_perm:[1,0,3,2] row_mask:0xf bank_mask:0xf
	s_nop 1
	s_waitcnt lgkmcnt(0)
	v_add_f32_dpp v131, v131, v131 quad_perm:[2,3,0,1] row_mask:0xf bank_mask:0xf
	s_nop 1
	s_waitcnt lgkmcnt(0)
	v_add_f32_dpp v131, v131, v131 row_half_mirror row_mask:0xf bank_mask:0xf
	v_cndmask_b32_e64 v133, v163, v131, s[60:61]
	s_nop 1
	s_waitcnt lgkmcnt(0)
	v_add_f32_dpp v131, v139, v139 quad_perm:[1,0,3,2] row_mask:0xf bank_mask:0xf
	s_nop 1
	s_waitcnt lgkmcnt(0)
	v_add_f32_dpp v131, v131, v131 quad_perm:[2,3,0,1] row_mask:0xf bank_mask:0xf
	s_nop 1
	s_waitcnt lgkmcnt(0)
	v_add_f32_dpp v131, v131, v131 row_half_mirror row_mask:0xf bank_mask:0xf
	v_cndmask_b32_e64 v140, v165, v131, s[60:61]
	s_nop 1
	s_waitcnt lgkmcnt(0)
	v_add_f32_dpp v131, v141, v141 quad_perm:[1,0,3,2] row_mask:0xf bank_mask:0xf
	s_nop 1
	s_waitcnt lgkmcnt(0)
	v_add_f32_dpp v131, v131, v131 quad_perm:[2,3,0,1] row_mask:0xf bank_mask:0xf
	s_nop 1
	s_waitcnt lgkmcnt(0)
	v_add_f32_dpp v131, v131, v131 row_half_mirror row_mask:0xf bank_mask:0xf
	v_cndmask_b32_e64 v139, v167, v131, s[60:61]
	s_nop 1
	v_add_u32_e32 v132, s6, v142
	s_waitcnt lgkmcnt(0)
	v_add_f32_dpp v130, v130, v130 quad_perm:[1,0,3,2] row_mask:0xf bank_mask:0xf
	s_nop 1
	s_waitcnt lgkmcnt(0)
	v_add_f32_dpp v130, v130, v130 quad_perm:[2,3,0,1] row_mask:0xf bank_mask:0xf
	s_nop 1
	s_waitcnt lgkmcnt(0)
	v_add_f32_dpp v130, v130, v130 row_half_mirror row_mask:0xf bank_mask:0xf
	v_cndmask_b32_e64 v138, v169, v130, s[60:61]
	v_lshlrev_b64 v[130:131], 12, v[148:149]
	v_lshl_add_u64 v[134:135], s[70:71], 0, v[130:131]
	v_lshl_add_u64 v[130:131], v[144:145], 2, s[0:1]
	s_lshl_b64 s[0:1], s[64:65], 2
	s_add_u32 s0, s24, s0
	s_addc_u32 s1, s25, s1
	v_lshl_add_u64 v[130:131], v[130:131], 0, v[48:49]
	global_load_dword v48, v49, s[0:1]
	s_add_i32 s9, s9, s36
	s_mov_b32 s64, 0x3f2aaaab
	s_waitcnt vmcnt(0)
	v_fmac_f32_e32 v133, v48, v136
	v_lshlrev_b32_e32 v48, 16, v223
	v_mul_f32_e32 v136, 0xbfb8aa3b, v48
	v_exp_f32_e32 v136, v136
	s_nop 0
	v_add_f32_e32 v136, 1.0, v136
	v_rcp_f32_e32 v136, v136
	s_nop 0
	v_mul_f32_e32 v48, v136, v48
	v_mul_f32_e32 v48, v48, v133
	v_ashrrev_i32_e32 v133, 31, v132
	v_cvt_pk_bf16_f32 v48, v48, v49
	v_lshl_add_u64 v[132:133], v[132:133], 1, v[134:135]
	global_store_short v[132:133], v48, off
	global_store_dwordx4 v[130:131], v[102:105], off
	global_store_dwordx4 v[130:131], v[110:113], off offset:128
	global_store_dwordx4 v[130:131], v[118:121], off offset:256
	global_store_dwordx4 v[130:131], v[126:129], off offset:384
	global_load_dword v48, v49, s[0:1] offset:4
	v_mov_b64_e32 v[112:113], v[26:27]
	v_mov_b64_e32 v[128:129], v[30:31]
	v_mov_b64_e32 v[120:121], v[60:61]
	v_mov_b64_e32 v[126:127], v[28:29]
	v_mov_b64_e32 v[110:111], v[24:25]
	v_mov_b64_e32 v[118:119], v[58:59]
	s_waitcnt vmcnt(0)
	v_fmac_f32_e32 v140, v48, v137
	v_lshlrev_b32_e32 v48, 16, v222
	v_mul_f32_e32 v102, 0xbfb8aa3b, v48
	v_exp_f32_e32 v102, v102
	v_mov_b64_e32 v[136:137], v[64:65]
	v_mov_b64_e32 v[134:135], v[62:63]
	v_add_f32_e32 v102, 1.0, v102
	v_rcp_f32_e32 v102, v102
	s_nop 0
	v_mul_f32_e32 v48, v102, v48
	v_add_co_u32_e32 v102, vcc, s17, v130
	v_mul_f32_e32 v48, v48, v140
	s_nop 0
	v_addc_co_u32_e32 v103, vcc, 0, v131, vcc
	v_cvt_pk_bf16_f32 v48, v48, v49
	global_store_short v[132:133], v48, off offset:128
	global_store_dwordx4 v[102:103], v[98:101], off
	global_store_dwordx4 v[102:103], v[106:109], off offset:128
	global_store_dwordx4 v[102:103], v[114:117], off offset:256
	global_store_dwordx4 v[102:103], v[122:125], off offset:384
	global_load_dword v48, v49, s[0:1] offset:8
	ds_read2st64_b32 v[98:99], v220 offset0:2 offset1:3
	v_add_co_u32_e32 v100, vcc, s13, v130
	v_mov_b64_e32 v[124:125], v[14:15]
	s_nop 0
	v_addc_co_u32_e32 v101, vcc, 0, v131, vcc
	v_mov_b64_e32 v[108:109], v[10:11]
	v_mov_b64_e32 v[116:117], v[42:43]
	v_mov_b64_e32 v[104:105], v[56:57]
	v_mov_b64_e32 v[122:123], v[12:13]
	v_mov_b64_e32 v[106:107], v[8:9]
	v_mov_b64_e32 v[114:115], v[40:41]
	v_mov_b64_e32 v[102:103], v[54:55]
	s_waitcnt vmcnt(0) lgkmcnt(0)
	v_fmac_f32_e32 v139, v48, v98
	v_lshlrev_b32_e32 v48, 16, v221
	v_mul_f32_e32 v98, 0xbfb8aa3b, v48
	v_exp_f32_e32 v98, v98
	s_nop 0
	v_add_f32_e32 v98, 1.0, v98
	v_rcp_f32_e32 v98, v98
	s_nop 0
	v_mul_f32_e32 v48, v98, v48
	v_mul_f32_e32 v48, v48, v139
	v_cvt_pk_bf16_f32 v48, v48, v49
	global_store_short v[132:133], v48, off offset:256
	global_store_dwordx4 v[100:101], v[82:85], off
	global_store_dwordx4 v[100:101], v[86:89], off offset:128
	global_store_dwordx4 v[100:101], v[90:93], off offset:256
	global_store_dwordx4 v[100:101], v[94:97], off offset:384
	global_load_dword v48, v49, s[0:1] offset:12
	v_mov_b64_e32 v[92:93], v[6:7]
	v_mov_b64_e32 v[96:97], v[22:23]
	v_mov_b64_e32 v[88:89], v[52:53]
	v_mov_b64_e32 v[90:91], v[4:5]
	v_mov_b64_e32 v[94:95], v[20:21]
	v_mov_b64_e32 v[86:87], v[50:51]
	s_waitcnt vmcnt(0)
	v_fmac_f32_e32 v138, v48, v99
	v_lshlrev_b32_e32 v48, 16, v207
	v_mul_f32_e32 v82, 0xbfb8aa3b, v48
	v_exp_f32_e32 v82, v82
	v_mov_b64_e32 v[100:101], v[38:39]
	v_mov_b64_e32 v[98:99], v[36:37]
	v_add_f32_e32 v82, 1.0, v82
	v_rcp_f32_e32 v82, v82
	s_nop 0
	v_mul_f32_e32 v48, v82, v48
	v_add_co_u32_e32 v82, vcc, s37, v130
	v_mul_f32_e32 v48, v48, v138
	s_nop 0
	v_addc_co_u32_e32 v83, vcc, 0, v131, vcc
	v_cvt_pk_bf16_f32 v48, v48, v49
	global_store_short v[132:133], v48, off offset:384
	global_store_dwordx4 v[82:83], v[66:69], off
	global_store_dwordx4 v[82:83], v[70:73], off offset:128
	global_store_dwordx4 v[82:83], v[74:77], off offset:256
	global_store_dwordx4 v[82:83], v[78:81], off offset:384
	v_mov_b64_e32 v[132:133], v[46:47]
	v_mov_b64_e32 v[76:77], v[2:3]
	v_mov_b64_e32 v[80:81], v[18:19]
	v_mov_b64_e32 v[84:85], v[34:35]
	s_andn2_b64 vcc, exec, s[40:41]
	v_mov_b64_e32 v[74:75], v[0:1]
	v_mov_b64_e32 v[78:79], v[16:17]
	v_mov_b64_e32 v[130:131], v[44:45]
	v_mov_b64_e32 v[82:83], v[32:33]
	s_cbranch_vccz .LBB0_841
